# aggfuse with 4-row batched exp in the in-epilogue chunk-aggregate scan (hide transcendental latency)
# baseline (speedup 1.0000x reference)
; __device__ __forceinline__ float bf_lo(unsigned w) { return __uint_as_float(w << 16); }
; __device__ __forceinline__ float bf_hi(unsigned w) { return __uint_as_float(w & 0xffff0000u); }
;     __device__ __forceinline__ void operator()(EPI_ARGS) const {
;         const int c0 = (u.pn >> 1) * 256 + (u.pn & 1) * 128 + wc * 32 + 8 * fq;
;         u32x4 vv[2][4];
; #pragma unroll
;         for (int ai = 0; ai < 2; ++ai)
; #pragma unroll
;             for (int m = 0; m < 4; ++m) vv[ai][m] = *(const u32x4*)(V + (size_t)ROW_OF(ai, m) * LW + c0);
;         f32x4 ba[2], bi[2], sp[2];
; #pragma unroll
;         for (int n = 0; n < 2; ++n) { ba[n] = *(const f32x4*)(b_a + c0 + 4 * n); bi[n] = *(const f32x4*)(b_i + c0 + 4 * n); sp[n] = *(const f32x4*)(sp8 + c0 + 4 * n); }
; #pragma unroll
;         for (int ai = 0; ai < 2; ++ai)
; #pragma unroll
;             for (int m = 0; m < 4; ++m) {
;                 const int row = ROW_OF(ai, m);
; #pragma unroll
;                 for (int n = 0; n < 2; ++n) {
;                     const unsigned w0 = n ? vv[ai][m].z : vv[ai][m].x, w1 = n ? vv[ai][m].w : vv[ai][m].y;
;                     const f32x4 vx = (f32x4){bf_lo(w0), bf_hi(w0), bf_lo(w1), bf_hi(w1)};
;                     const f32x4 r = sigmoid4(acc[ai][0][m][n] + ba[n]), ig = sigmoid4(acc[ai][1][m][n] + bi[n]);
;                     const f32x4 la = sp[n] * r * (-1.4426950409f);
;                     f32x4 av;
; #pragma unroll
;                     for (int j = 0; j < 4; ++j) av[j] = __builtin_amdgcn_exp2f(la[j]);
;                     const f32x4 om = 1.0f - av * av; f32x4 sq;
; #pragma unroll
;                     for (int j = 0; j < 4; ++j) sq[j] = __builtin_amdgcn_sqrtf(om[j]);
;                     const f32x4 bx = sq * ig * vx;
.LBB0_556:
	v_mov_b32_e32 v65, v215
	v_mov_b32_e32 v64, v216
	s_lshl_b32 s0, s27, 7
	s_or_b32 s0, s0, s21
	v_lshl_add_u32 v64, v64, 3, s0
	s_lshl_b32 s0, s74, 8
	s_add_i32 s0, s0, s19
	v_add_u32_e32 v68, s0, v65
	v_ashrrev_i32_e32 v65, 31, v64
	v_ashrrev_i32_e32 v69, 31, v68
	v_lshl_add_u64 v[70:71], v[64:65], 1, s[54:55]
	v_lshlrev_b64 v[66:67], 12, v[68:69]
	v_lshlrev_b64 v[196:197], 2, v[64:65]
	v_lshl_add_u64 v[66:67], v[70:71], 0, v[66:67]
	v_lshl_add_u64 v[64:65], s[38:39], 0, v[196:197]
	global_load_dwordx4 v[180:183], v[66:67], off
	global_load_dwordx4 v[100:103], v[64:65], off
	v_lshl_add_u64 v[66:67], s[42:43], 0, v[196:197]
	global_load_dwordx4 v[92:95], v[66:67], off
	v_lshl_add_u64 v[108:109], s[56:57], 0, v[196:197]
	global_load_dwordx4 v[88:91], v[108:109], off
	global_load_dwordx4 v[80:83], v[64:65], off offset:16
	global_load_dwordx4 v[72:75], v[66:67], off offset:16
	s_nop 0
	global_load_dwordx4 v[64:67], v[108:109], off offset:16
	v_add_u32_e32 v210, 16, v68
	v_add_u32_e32 v208, 32, v68
	v_add_u32_e32 v206, 48, v68
	v_add_u32_e32 v204, 0x80, v68
	v_add_u32_e32 v202, 0x90, v68
	v_add_u32_e32 v200, 0xa0, v68
	v_add_u32_e32 v198, 0xb0, v68
	v_ashrrev_i32_e32 v211, 31, v210
	v_ashrrev_i32_e32 v209, 31, v208
	v_ashrrev_i32_e32 v207, 31, v206
	v_ashrrev_i32_e32 v205, 31, v204
	v_ashrrev_i32_e32 v203, 31, v202
	v_ashrrev_i32_e32 v201, 31, v200
	v_ashrrev_i32_e32 v199, 31, v198
	v_lshlrev_b64 v[222:223], 13, v[68:69]
	v_lshlrev_b64 v[68:69], 12, v[210:211]
	v_lshlrev_b64 v[108:109], 12, v[208:209]
	v_lshlrev_b64 v[110:111], 12, v[206:207]
	v_lshlrev_b64 v[128:129], 12, v[204:205]
	v_lshlrev_b64 v[130:131], 12, v[202:203]
	v_lshlrev_b64 v[148:149], 12, v[200:201]
	v_lshlrev_b64 v[150:151], 12, v[198:199]
	v_lshl_add_u64 v[68:69], v[70:71], 0, v[68:69]
	v_lshl_add_u64 v[108:109], v[70:71], 0, v[108:109]
	v_lshl_add_u64 v[110:111], v[70:71], 0, v[110:111]
	v_lshl_add_u64 v[128:129], v[70:71], 0, v[128:129]
	v_lshl_add_u64 v[130:131], v[70:71], 0, v[130:131]
	v_lshl_add_u64 v[224:225], v[70:71], 0, v[148:149]
	v_lshl_add_u64 v[70:71], v[70:71], 0, v[150:151]
	global_load_dwordx4 v[176:179], v[68:69], off
	global_load_dwordx4 v[172:175], v[108:109], off
	global_load_dwordx4 v[164:167], v[110:111], off
	global_load_dwordx4 v[148:151], v[128:129], off
	s_nop 0
	global_load_dwordx4 v[128:131], v[130:131], off
	s_nop 0
	global_load_dwordx4 v[108:111], v[224:225], off
	s_nop 0
	global_load_dwordx4 v[68:71], v[70:71], off
	v_readlane_b32 s80, v248, 11
	v_readlane_b32 s92, v248, 23
	v_readlane_b32 s93, v248, 24
	v_readlane_b32 s81, v248, 12
	v_readlane_b32 s82, v248, 13
	v_readlane_b32 s83, v248, 14
	v_readlane_b32 s84, v248, 15
	v_readlane_b32 s85, v248, 16
	v_readlane_b32 s86, v248, 17
	v_readlane_b32 s87, v248, 18
	v_readlane_b32 s88, v248, 19
	v_readlane_b32 s89, v248, 20
	v_readlane_b32 s90, v248, 21
	v_readlane_b32 s91, v248, 22
	v_readlane_b32 s94, v248, 25
	v_readlane_b32 s95, v248, 26
	s_and_b64 vcc, exec, s[4:5]
	s_mov_b64 s[0:1], -1
	s_waitcnt vmcnt(0)
	v_lshlrev_b32_e32 v224, 16, v180
	v_pk_add_f32 v[168:169], v[168:169], v[100:101]
	v_pk_add_f32 v[170:171], v[170:171], v[102:103]
	v_pk_add_f32 v[160:161], v[160:161], v[92:93]
	v_mul_f32_e32 v168, 0xbfb8aa3b, v168
	v_mul_f32_e32 v169, 0xbfb8aa3b, v169
	v_mul_f32_e32 v170, 0xbfb8aa3b, v170
	v_mul_f32_e32 v171, 0xbfb8aa3b, v171
	v_mul_f32_e32 v160, 0xbfb8aa3b, v160
	v_mul_f32_e32 v161, 0xbfb8aa3b, v161
	v_exp_f32_e32 v168, v168
	v_exp_f32_e32 v169, v169
	v_pk_add_f32 v[162:163], v[162:163], v[94:95]
	v_exp_f32_e32 v170, v170
	v_exp_f32_e32 v171, v171
	v_exp_f32_e32 v160, v160
	v_exp_f32_e32 v161, v161
	v_mul_f32_e32 v162, 0xbfb8aa3b, v162
	v_mul_f32_e32 v163, 0xbfb8aa3b, v163
	v_exp_f32_e32 v162, v162
	v_and_b32_e32 v225, 0xffff0000, v180
	v_exp_f32_e32 v180, v163
	v_add_f32_e32 v163, 1.0, v168
	v_add_f32_e32 v168, 1.0, v169
	v_add_f32_e32 v169, 1.0, v170
	v_add_f32_e32 v170, 1.0, v171
	v_add_f32_e32 v171, 1.0, v160
	v_add_f32_e32 v221, 1.0, v161
	v_rcp_f32_e32 v160, v163
	v_rcp_f32_e32 v161, v168
	v_add_f32_e32 v226, 1.0, v162
	v_rcp_f32_e32 v162, v169
	v_rcp_f32_e32 v163, v170
	v_pk_mul_f32 v[160:161], v[88:89], v[160:161]
	v_rcp_f32_e32 v170, v226
	v_pk_mul_f32 v[160:161], v[160:161], s[62:63] op_sel_hi:[1,0]
	v_pk_mul_f32 v[162:163], v[90:91], v[162:163]
	v_exp_f32_e32 v226, v160
	v_exp_f32_e32 v227, v161
	v_pk_mul_f32 v[162:163], v[162:163], s[62:63] op_sel_hi:[1,0]
	v_pk_add_f32 v[156:157], v[156:157], v[80:81]
	v_exp_f32_e32 v228, v162
	v_exp_f32_e32 v229, v163
	v_pk_add_f32 v[158:159], v[158:159], v[82:83]
	v_mul_f32_e32 v156, 0xbfb8aa3b, v156
	v_mul_f32_e32 v157, 0xbfb8aa3b, v157
	v_pk_mul_f32 v[226:227], v[226:227], v[226:227]
	v_exp_f32_e32 v156, v156
	v_exp_f32_e32 v157, v157
	v_mul_f32_e32 v158, 0xbfb8aa3b, v158
	v_mul_f32_e32 v159, 0xbfb8aa3b, v159
	v_rcp_f32_e32 v168, v171
	v_add_f32_e32 v171, 1.0, v180
	v_sub_f32_e32 v180, 1.0, v226
	v_exp_f32_e32 v158, v158
	v_exp_f32_e32 v159, v159
	v_pk_mul_f32 v[228:229], v[228:229], v[228:229]
	v_sqrt_f32_e32 v226, v180
	v_sub_f32_e32 v180, 1.0, v227
	v_rcp_f32_e32 v169, v221
	v_sub_f32_e32 v221, 1.0, v228
	v_sqrt_f32_e32 v227, v180
	v_sqrt_f32_e32 v228, v221
	v_sub_f32_e32 v221, 1.0, v229
	v_add_f32_e32 v156, 1.0, v156
	v_add_f32_e32 v157, 1.0, v157
	v_rcp_f32_e32 v171, v171
	v_sqrt_f32_e32 v229, v221
	v_rcp_f32_e32 v156, v156
	v_rcp_f32_e32 v157, v157
	v_add_f32_e32 v158, 1.0, v158
	v_add_f32_e32 v159, 1.0, v159
	v_rcp_f32_e32 v158, v158
	v_rcp_f32_e32 v159, v159
	v_pk_mul_f32 v[168:169], v[168:169], v[226:227]
	v_lshlrev_b32_e32 v180, 16, v181
	v_pk_mul_f32 v[168:169], v[168:169], v[224:225]
	v_and_b32_e32 v181, 0xffff0000, v181
; __device__ __forceinline__ unsigned cvt_pk_bf16(float lo, float hi) { unsigned r; asm volatile("v_cvt_pk_bf16_f32 %0, %1, %2" : "=v"(r) : "v"(lo), "v"(hi)); return r; }
; __device__ __forceinline__ float bf_lo(unsigned w) { return __uint_as_float(w << 16); }
; __device__ __forceinline__ float bf_hi(unsigned w) { return __uint_as_float(w & 0xffff0000u); }
;     __device__ __forceinline__ void operator()(EPI_ARGS) const {
;     ...
;         for (int ai = 0; ai < 2; ++ai)
; #pragma unroll
;             for (int m = 0; m < 4; ++m) {
;                 const int row = ROW_OF(ai, m);
; #pragma unroll
;                 for (int n = 0; n < 2; ++n) {
;                     const unsigned w0 = n ? vv[ai][m].z : vv[ai][m].x, w1 = n ? vv[ai][m].w : vv[ai][m].y;
;                     const f32x4 vx = (f32x4){bf_lo(w0), bf_hi(w0), bf_lo(w1), bf_hi(w1)};
;                     const f32x4 r = sigmoid4(acc[ai][0][m][n] + ba[n]), ig = sigmoid4(acc[ai][1][m][n] + bi[n]);
;                     const f32x4 la = sp[n] * r * (-1.4426950409f);
;                     f32x4 av;
; #pragma unroll
;                     for (int j = 0; j < 4; ++j) av[j] = __builtin_amdgcn_exp2f(la[j]);
;                     const f32x4 om = 1.0f - av * av; f32x4 sq;
; #pragma unroll
;                     for (int j = 0; j < 4; ++j) sq[j] = __builtin_amdgcn_sqrtf(om[j]);
;                     const f32x4 bx = sq * ig * vx;
;                     u32x4 w; w.x = cvt_pk_bf16(la[0], bx[0]); w.y = cvt_pk_bf16(la[1], bx[1]); w.z = cvt_pk_bf16(la[2], bx[2]); w.w = cvt_pk_bf16(la[3], bx[3]);
;                     *(u32x4*)(AB + (size_t)row * LW + c0 + 4 * n) = w;
	v_pk_mul_f32 v[170:171], v[170:171], v[228:229]
	v_cvt_pk_bf16_f32 v160, v160, v168
	v_cvt_pk_bf16_f32 v161, v161, v169
	v_lshl_add_u64 v[168:169], s[92:93], 0, v[222:223]
	v_pk_mul_f32 v[156:157], v[64:65], v[156:157]
	v_pk_mul_f32 v[170:171], v[170:171], v[180:181]
	v_lshl_add_u64 v[168:169], v[168:169], 0, v[196:197]
	v_cvt_pk_bf16_f32 v162, v162, v170
	v_cvt_pk_bf16_f32 v163, v163, v171
	v_pk_add_f32 v[152:153], v[152:153], v[72:73]
	v_pk_mul_f32 v[158:159], v[66:67], v[158:159]
	v_pk_mul_f32 v[156:157], v[156:157], s[62:63] op_sel_hi:[1,0]
	v_pk_add_f32 v[144:145], v[144:145], v[100:101]
	global_store_dwordx4 v[168:169], v[160:163], off
	v_pk_add_f32 v[154:155], v[154:155], v[74:75]
	v_mul_f32_e32 v152, 0xbfb8aa3b, v152
	v_mul_f32_e32 v153, 0xbfb8aa3b, v153
	v_pk_mul_f32 v[158:159], v[158:159], s[62:63] op_sel_hi:[1,0]
	v_exp_f32_e32 v162, v156
	v_exp_f32_e32 v163, v157
	v_pk_add_f32 v[146:147], v[146:147], v[102:103]
	v_mul_f32_e32 v144, 0xbfb8aa3b, v144
	v_mul_f32_e32 v145, 0xbfb8aa3b, v145
	v_exp_f32_e32 v152, v152
	v_exp_f32_e32 v153, v153
	v_mul_f32_e32 v154, 0xbfb8aa3b, v154
	v_mul_f32_e32 v155, 0xbfb8aa3b, v155
	v_exp_f32_e32 v170, v158
	v_exp_f32_e32 v171, v159
	v_exp_f32_e32 v144, v144
	v_exp_f32_e32 v145, v145
	v_mul_f32_e32 v146, 0xbfb8aa3b, v146
	v_mul_f32_e32 v147, 0xbfb8aa3b, v147
	v_exp_f32_e32 v154, v154
	v_exp_f32_e32 v155, v155
	v_exp_f32_e32 v146, v146
	v_exp_f32_e32 v147, v147
	v_pk_mul_f32 v[162:163], v[162:163], v[162:163]
	v_add_f32_e32 v152, 1.0, v152
	v_add_f32_e32 v153, 1.0, v153
	v_pk_mul_f32 v[170:171], v[170:171], v[170:171]
	v_sub_f32_e32 v162, 1.0, v162
	v_sub_f32_e32 v163, 1.0, v163
	v_add_f32_e32 v144, 1.0, v144
	v_add_f32_e32 v145, 1.0, v145
	v_rcp_f32_e32 v152, v152
	v_rcp_f32_e32 v153, v153
	v_add_f32_e32 v154, 1.0, v154
	v_add_f32_e32 v155, 1.0, v155
	v_sqrt_f32_e32 v162, v162
	v_sub_f32_e32 v170, 1.0, v170
	v_sub_f32_e32 v171, 1.0, v171
	v_sqrt_f32_e32 v163, v163
	v_rcp_f32_e32 v144, v144
	v_rcp_f32_e32 v145, v145
	v_add_f32_e32 v146, 1.0, v146
	v_add_f32_e32 v147, 1.0, v147
	v_rcp_f32_e32 v154, v154
	v_rcp_f32_e32 v155, v155
	v_sqrt_f32_e32 v170, v170
	v_sqrt_f32_e32 v171, v171
	v_rcp_f32_e32 v146, v146
	v_rcp_f32_e32 v147, v147
	v_lshlrev_b32_e32 v160, 16, v182
	v_and_b32_e32 v161, 0xffff0000, v182
	v_pk_mul_f32 v[152:153], v[152:153], v[162:163]
	v_pk_mul_f32 v[144:145], v[88:89], v[144:145]
	v_lshlrev_b32_e32 v180, 16, v183
	v_and_b32_e32 v181, 0xffff0000, v183
	v_pk_mul_f32 v[154:155], v[154:155], v[170:171]
	v_pk_mul_f32 v[152:153], v[152:153], v[160:161]
	v_pk_add_f32 v[140:141], v[140:141], v[92:93]
	v_pk_mul_f32 v[146:147], v[90:91], v[146:147]
	v_pk_mul_f32 v[144:145], v[144:145], s[62:63] op_sel_hi:[1,0]
	v_pk_mul_f32 v[154:155], v[154:155], v[180:181]
	v_cvt_pk_bf16_f32 v152, v156, v152
	v_cvt_pk_bf16_f32 v153, v157, v153
	v_pk_add_f32 v[142:143], v[142:143], v[94:95]
	v_mul_f32_e32 v140, 0xbfb8aa3b, v140
	v_mul_f32_e32 v141, 0xbfb8aa3b, v141
	v_pk_mul_f32 v[146:147], v[146:147], s[62:63] op_sel_hi:[1,0]
	v_exp_f32_e32 v156, v144
	v_exp_f32_e32 v157, v145
	v_cvt_pk_bf16_f32 v154, v158, v154
	v_cvt_pk_bf16_f32 v155, v159, v155
	v_exp_f32_e32 v140, v140
	v_exp_f32_e32 v141, v141
	v_mul_f32_e32 v142, 0xbfb8aa3b, v142
	v_mul_f32_e32 v143, 0xbfb8aa3b, v143
	v_exp_f32_e32 v158, v146
	v_exp_f32_e32 v159, v147
	v_pk_add_f32 v[136:137], v[136:137], v[80:81]
	v_exp_f32_e32 v142, v142
	v_exp_f32_e32 v143, v143
	v_pk_add_f32 v[138:139], v[138:139], v[82:83]
	v_mul_f32_e32 v136, 0xbfb8aa3b, v136
	v_mul_f32_e32 v137, 0xbfb8aa3b, v137
	v_exp_f32_e32 v136, v136
	v_exp_f32_e32 v137, v137
	v_mul_f32_e32 v138, 0xbfb8aa3b, v138
	v_mul_f32_e32 v139, 0xbfb8aa3b, v139
	v_pk_mul_f32 v[156:157], v[156:157], v[156:157]
	v_exp_f32_e32 v138, v138
	v_exp_f32_e32 v139, v139
	v_add_f32_e32 v140, 1.0, v140
	v_add_f32_e32 v141, 1.0, v141
	v_pk_mul_f32 v[158:159], v[158:159], v[158:159]
	v_sub_f32_e32 v156, 1.0, v156
	v_sub_f32_e32 v157, 1.0, v157
	v_rcp_f32_e32 v140, v140
	v_rcp_f32_e32 v141, v141
	v_add_f32_e32 v142, 1.0, v142
	v_add_f32_e32 v143, 1.0, v143
	v_sqrt_f32_e32 v156, v156
	v_sub_f32_e32 v158, 1.0, v158
	v_sub_f32_e32 v159, 1.0, v159
	v_sqrt_f32_e32 v157, v157
	v_rcp_f32_e32 v142, v142
	v_rcp_f32_e32 v143, v143
	v_sqrt_f32_e32 v158, v158
	v_sqrt_f32_e32 v159, v159
	v_add_f32_e32 v136, 1.0, v136
	v_add_f32_e32 v137, 1.0, v137
	v_rcp_f32_e32 v136, v136
	v_rcp_f32_e32 v137, v137
	v_add_f32_e32 v138, 1.0, v138
	v_add_f32_e32 v139, 1.0, v139
	v_rcp_f32_e32 v138, v138
	v_rcp_f32_e32 v139, v139
	global_store_dwordx4 v[168:169], v[152:155], off offset:16
	v_pk_mul_f32 v[140:141], v[140:141], v[156:157]
	v_lshlrev_b32_e32 v160, 16, v177
	v_lshlrev_b32_e32 v154, 16, v176
	v_and_b32_e32 v155, 0xffff0000, v176
	v_lshlrev_b64 v[152:153], 13, v[210:211]
	v_and_b32_e32 v161, 0xffff0000, v177
	v_pk_mul_f32 v[142:143], v[142:143], v[158:159]
	v_pk_mul_f32 v[140:141], v[140:141], v[154:155]
	v_pk_mul_f32 v[142:143], v[142:143], v[160:161]
	v_cvt_pk_bf16_f32 v140, v144, v140
	v_cvt_pk_bf16_f32 v141, v145, v141
	v_lshl_add_u64 v[144:145], s[92:93], 0, v[152:153]
	v_pk_mul_f32 v[136:137], v[64:65], v[136:137]
	v_cvt_pk_bf16_f32 v142, v146, v142
	v_cvt_pk_bf16_f32 v143, v147, v143
	v_lshl_add_u64 v[144:145], v[144:145], 0, v[196:197]
	v_pk_add_f32 v[132:133], v[132:133], v[72:73]
	v_pk_mul_f32 v[138:139], v[66:67], v[138:139]
	v_pk_mul_f32 v[136:137], v[136:137], s[62:63] op_sel_hi:[1,0]
	v_pk_add_f32 v[124:125], v[124:125], v[100:101]
	global_store_dwordx4 v[144:145], v[140:143], off
	v_pk_add_f32 v[134:135], v[134:135], v[74:75]
	v_mul_f32_e32 v132, 0xbfb8aa3b, v132
	v_mul_f32_e32 v133, 0xbfb8aa3b, v133
; __device__ __forceinline__ unsigned cvt_pk_bf16(float lo, float hi) { unsigned r; asm volatile("v_cvt_pk_bf16_f32 %0, %1, %2" : "=v"(r) : "v"(lo), "v"(hi)); return r; }
; __device__ __forceinline__ float bf_lo(unsigned w) { return __uint_as_float(w << 16); }
; __device__ __forceinline__ float bf_hi(unsigned w) { return __uint_as_float(w & 0xffff0000u); }
;     __device__ __forceinline__ void operator()(EPI_ARGS) const {
;     ...
;         for (int ai = 0; ai < 2; ++ai)
; #pragma unroll
;             for (int m = 0; m < 4; ++m) {
;                 const int row = ROW_OF(ai, m);
; #pragma unroll
;                 for (int n = 0; n < 2; ++n) {
;                     const unsigned w0 = n ? vv[ai][m].z : vv[ai][m].x, w1 = n ? vv[ai][m].w : vv[ai][m].y;
;                     const f32x4 vx = (f32x4){bf_lo(w0), bf_hi(w0), bf_lo(w1), bf_hi(w1)};
;                     const f32x4 r = sigmoid4(acc[ai][0][m][n] + ba[n]), ig = sigmoid4(acc[ai][1][m][n] + bi[n]);
;                     const f32x4 la = sp[n] * r * (-1.4426950409f);
;                     f32x4 av;
; #pragma unroll
;                     for (int j = 0; j < 4; ++j) av[j] = __builtin_amdgcn_exp2f(la[j]);
;                     const f32x4 om = 1.0f - av * av; f32x4 sq;
; #pragma unroll
;                     for (int j = 0; j < 4; ++j) sq[j] = __builtin_amdgcn_sqrtf(om[j]);
;                     const f32x4 bx = sq * ig * vx;
;                     u32x4 w; w.x = cvt_pk_bf16(la[0], bx[0]); w.y = cvt_pk_bf16(la[1], bx[1]); w.z = cvt_pk_bf16(la[2], bx[2]); w.w = cvt_pk_bf16(la[3], bx[3]);
;                     *(u32x4*)(AB + (size_t)row * LW + c0 + 4 * n) = w;
	v_pk_mul_f32 v[138:139], v[138:139], s[62:63] op_sel_hi:[1,0]
	v_exp_f32_e32 v142, v136
	v_exp_f32_e32 v143, v137
	v_pk_add_f32 v[126:127], v[126:127], v[102:103]
	v_mul_f32_e32 v124, 0xbfb8aa3b, v124
	v_mul_f32_e32 v125, 0xbfb8aa3b, v125
	v_exp_f32_e32 v132, v132
	v_exp_f32_e32 v133, v133
	v_mul_f32_e32 v134, 0xbfb8aa3b, v134
	v_mul_f32_e32 v135, 0xbfb8aa3b, v135
	v_exp_f32_e32 v146, v138
	v_exp_f32_e32 v147, v139
	v_exp_f32_e32 v124, v124
	v_exp_f32_e32 v125, v125
	v_mul_f32_e32 v126, 0xbfb8aa3b, v126
	v_mul_f32_e32 v127, 0xbfb8aa3b, v127
	v_exp_f32_e32 v134, v134
	v_exp_f32_e32 v135, v135
	v_exp_f32_e32 v126, v126
	v_exp_f32_e32 v127, v127
	v_pk_mul_f32 v[142:143], v[142:143], v[142:143]
	v_add_f32_e32 v132, 1.0, v132
	v_add_f32_e32 v133, 1.0, v133
	v_pk_mul_f32 v[146:147], v[146:147], v[146:147]
	v_sub_f32_e32 v142, 1.0, v142
	v_sub_f32_e32 v143, 1.0, v143
	v_add_f32_e32 v124, 1.0, v124
	v_add_f32_e32 v125, 1.0, v125
	v_rcp_f32_e32 v132, v132
	v_rcp_f32_e32 v133, v133
	v_add_f32_e32 v134, 1.0, v134
	v_add_f32_e32 v135, 1.0, v135
	v_sqrt_f32_e32 v142, v142
	v_sub_f32_e32 v146, 1.0, v146
	v_sub_f32_e32 v147, 1.0, v147
	v_sqrt_f32_e32 v143, v143
	v_rcp_f32_e32 v124, v124
	v_rcp_f32_e32 v125, v125
	v_add_f32_e32 v126, 1.0, v126
	v_add_f32_e32 v127, 1.0, v127
	v_rcp_f32_e32 v134, v134
	v_rcp_f32_e32 v135, v135
	v_sqrt_f32_e32 v146, v146
	v_sqrt_f32_e32 v147, v147
	v_rcp_f32_e32 v126, v126
	v_rcp_f32_e32 v127, v127
	v_lshlrev_b32_e32 v140, 16, v178
	v_and_b32_e32 v141, 0xffff0000, v178
	v_pk_mul_f32 v[132:133], v[132:133], v[142:143]
	v_pk_mul_f32 v[124:125], v[88:89], v[124:125]
	v_lshlrev_b32_e32 v152, 16, v179
	v_and_b32_e32 v153, 0xffff0000, v179
	v_pk_mul_f32 v[134:135], v[134:135], v[146:147]
	v_pk_mul_f32 v[132:133], v[132:133], v[140:141]
	v_pk_add_f32 v[120:121], v[120:121], v[92:93]
	v_pk_mul_f32 v[126:127], v[90:91], v[126:127]
	v_pk_mul_f32 v[124:125], v[124:125], s[62:63] op_sel_hi:[1,0]
	v_pk_mul_f32 v[134:135], v[134:135], v[152:153]
	v_cvt_pk_bf16_f32 v132, v136, v132
	v_cvt_pk_bf16_f32 v133, v137, v133
	v_pk_add_f32 v[122:123], v[122:123], v[94:95]
	v_mul_f32_e32 v120, 0xbfb8aa3b, v120
	v_mul_f32_e32 v121, 0xbfb8aa3b, v121
	v_pk_mul_f32 v[126:127], v[126:127], s[62:63] op_sel_hi:[1,0]
	v_exp_f32_e32 v136, v124
	v_exp_f32_e32 v137, v125
	v_cvt_pk_bf16_f32 v134, v138, v134
	v_cvt_pk_bf16_f32 v135, v139, v135
	v_exp_f32_e32 v120, v120
	v_exp_f32_e32 v121, v121
	v_mul_f32_e32 v122, 0xbfb8aa3b, v122
	v_mul_f32_e32 v123, 0xbfb8aa3b, v123
	v_exp_f32_e32 v138, v126
	v_exp_f32_e32 v139, v127
	v_pk_add_f32 v[116:117], v[116:117], v[80:81]
	v_exp_f32_e32 v122, v122
	v_exp_f32_e32 v123, v123
	v_pk_add_f32 v[118:119], v[118:119], v[82:83]
	v_mul_f32_e32 v116, 0xbfb8aa3b, v116
	v_mul_f32_e32 v117, 0xbfb8aa3b, v117
	v_exp_f32_e32 v116, v116
	v_exp_f32_e32 v117, v117
	v_mul_f32_e32 v118, 0xbfb8aa3b, v118
	v_mul_f32_e32 v119, 0xbfb8aa3b, v119
	v_pk_mul_f32 v[136:137], v[136:137], v[136:137]
	v_exp_f32_e32 v118, v118
	v_exp_f32_e32 v119, v119
	v_add_f32_e32 v120, 1.0, v120
	v_add_f32_e32 v121, 1.0, v121
	v_pk_mul_f32 v[138:139], v[138:139], v[138:139]
	v_sub_f32_e32 v136, 1.0, v136
	v_sub_f32_e32 v137, 1.0, v137
	v_rcp_f32_e32 v120, v120
	v_rcp_f32_e32 v121, v121
	v_add_f32_e32 v122, 1.0, v122
	v_add_f32_e32 v123, 1.0, v123
	v_sqrt_f32_e32 v136, v136
	v_sub_f32_e32 v138, 1.0, v138
	v_sub_f32_e32 v139, 1.0, v139
	v_sqrt_f32_e32 v137, v137
	v_rcp_f32_e32 v122, v122
	v_rcp_f32_e32 v123, v123
	v_sqrt_f32_e32 v138, v138
	v_sqrt_f32_e32 v139, v139
	v_add_f32_e32 v116, 1.0, v116
	v_add_f32_e32 v117, 1.0, v117
	v_rcp_f32_e32 v116, v116
	v_rcp_f32_e32 v117, v117
	v_add_f32_e32 v118, 1.0, v118
	v_add_f32_e32 v119, 1.0, v119
	v_rcp_f32_e32 v118, v118
	v_rcp_f32_e32 v119, v119
	global_store_dwordx4 v[144:145], v[132:135], off offset:16
	v_pk_mul_f32 v[120:121], v[120:121], v[136:137]
	v_lshlrev_b32_e32 v140, 16, v173
	v_lshlrev_b32_e32 v134, 16, v172
	v_and_b32_e32 v135, 0xffff0000, v172
	v_lshlrev_b64 v[132:133], 13, v[208:209]
	v_and_b32_e32 v141, 0xffff0000, v173
	v_pk_mul_f32 v[122:123], v[122:123], v[138:139]
	v_pk_mul_f32 v[120:121], v[120:121], v[134:135]
	v_pk_mul_f32 v[122:123], v[122:123], v[140:141]
	v_cvt_pk_bf16_f32 v120, v124, v120
	v_cvt_pk_bf16_f32 v121, v125, v121
	v_lshl_add_u64 v[124:125], s[92:93], 0, v[132:133]
	v_pk_mul_f32 v[116:117], v[64:65], v[116:117]
	v_cvt_pk_bf16_f32 v122, v126, v122
	v_cvt_pk_bf16_f32 v123, v127, v123
	v_lshl_add_u64 v[124:125], v[124:125], 0, v[196:197]
	v_pk_add_f32 v[112:113], v[112:113], v[72:73]
	v_pk_mul_f32 v[118:119], v[66:67], v[118:119]
	v_pk_mul_f32 v[116:117], v[116:117], s[62:63] op_sel_hi:[1,0]
	v_pk_add_f32 v[104:105], v[104:105], v[100:101]
	global_store_dwordx4 v[124:125], v[120:123], off
	v_pk_add_f32 v[114:115], v[114:115], v[74:75]
	v_mul_f32_e32 v112, 0xbfb8aa3b, v112
	v_mul_f32_e32 v113, 0xbfb8aa3b, v113
	v_pk_mul_f32 v[118:119], v[118:119], s[62:63] op_sel_hi:[1,0]
	v_exp_f32_e32 v122, v116
	v_exp_f32_e32 v123, v117
	v_pk_add_f32 v[106:107], v[106:107], v[102:103]
	v_mul_f32_e32 v104, 0xbfb8aa3b, v104
	v_mul_f32_e32 v105, 0xbfb8aa3b, v105
	v_exp_f32_e32 v112, v112
	v_exp_f32_e32 v113, v113
	v_mul_f32_e32 v114, 0xbfb8aa3b, v114
	v_mul_f32_e32 v115, 0xbfb8aa3b, v115
	v_exp_f32_e32 v126, v118
	v_exp_f32_e32 v127, v119
	v_exp_f32_e32 v104, v104
	v_exp_f32_e32 v105, v105
	v_mul_f32_e32 v106, 0xbfb8aa3b, v106
	v_mul_f32_e32 v107, 0xbfb8aa3b, v107
	v_exp_f32_e32 v114, v114
	v_exp_f32_e32 v115, v115
	v_exp_f32_e32 v106, v106
	v_exp_f32_e32 v107, v107
	v_pk_mul_f32 v[122:123], v[122:123], v[122:123]
	v_add_f32_e32 v112, 1.0, v112
	v_add_f32_e32 v113, 1.0, v113
	v_pk_mul_f32 v[126:127], v[126:127], v[126:127]
; __device__ __forceinline__ unsigned cvt_pk_bf16(float lo, float hi) { unsigned r; asm volatile("v_cvt_pk_bf16_f32 %0, %1, %2" : "=v"(r) : "v"(lo), "v"(hi)); return r; }
; __device__ __forceinline__ float bf_lo(unsigned w) { return __uint_as_float(w << 16); }
; __device__ __forceinline__ float bf_hi(unsigned w) { return __uint_as_float(w & 0xffff0000u); }
;     __device__ __forceinline__ void operator()(EPI_ARGS) const {
;     ...
;         for (int ai = 0; ai < 2; ++ai)
; #pragma unroll
;             for (int m = 0; m < 4; ++m) {
;                 const int row = ROW_OF(ai, m);
; #pragma unroll
;                 for (int n = 0; n < 2; ++n) {
;                     const unsigned w0 = n ? vv[ai][m].z : vv[ai][m].x, w1 = n ? vv[ai][m].w : vv[ai][m].y;
;                     const f32x4 vx = (f32x4){bf_lo(w0), bf_hi(w0), bf_lo(w1), bf_hi(w1)};
;                     const f32x4 r = sigmoid4(acc[ai][0][m][n] + ba[n]), ig = sigmoid4(acc[ai][1][m][n] + bi[n]);
;                     const f32x4 la = sp[n] * r * (-1.4426950409f);
;                     f32x4 av;
; #pragma unroll
;                     for (int j = 0; j < 4; ++j) av[j] = __builtin_amdgcn_exp2f(la[j]);
;                     const f32x4 om = 1.0f - av * av; f32x4 sq;
; #pragma unroll
;                     for (int j = 0; j < 4; ++j) sq[j] = __builtin_amdgcn_sqrtf(om[j]);
;                     const f32x4 bx = sq * ig * vx;
;                     u32x4 w; w.x = cvt_pk_bf16(la[0], bx[0]); w.y = cvt_pk_bf16(la[1], bx[1]); w.z = cvt_pk_bf16(la[2], bx[2]); w.w = cvt_pk_bf16(la[3], bx[3]);
;                     *(u32x4*)(AB + (size_t)row * LW + c0 + 4 * n) = w;
	v_sub_f32_e32 v122, 1.0, v122
	v_sub_f32_e32 v123, 1.0, v123
	v_add_f32_e32 v104, 1.0, v104
	v_add_f32_e32 v105, 1.0, v105
	v_rcp_f32_e32 v112, v112
	v_rcp_f32_e32 v113, v113
	v_add_f32_e32 v114, 1.0, v114
	v_add_f32_e32 v115, 1.0, v115
	v_sqrt_f32_e32 v122, v122
	v_sub_f32_e32 v126, 1.0, v126
	v_sub_f32_e32 v127, 1.0, v127
	v_sqrt_f32_e32 v123, v123
	v_rcp_f32_e32 v104, v104
	v_rcp_f32_e32 v105, v105
	v_add_f32_e32 v106, 1.0, v106
	v_add_f32_e32 v107, 1.0, v107
	v_rcp_f32_e32 v114, v114
	v_rcp_f32_e32 v115, v115
	v_sqrt_f32_e32 v126, v126
	v_sqrt_f32_e32 v127, v127
	v_rcp_f32_e32 v106, v106
	v_rcp_f32_e32 v107, v107
	v_lshlrev_b32_e32 v120, 16, v174
	v_and_b32_e32 v121, 0xffff0000, v174
	v_pk_mul_f32 v[112:113], v[112:113], v[122:123]
	v_pk_mul_f32 v[104:105], v[88:89], v[104:105]
	v_lshlrev_b32_e32 v132, 16, v175
	v_and_b32_e32 v133, 0xffff0000, v175
	v_pk_mul_f32 v[114:115], v[114:115], v[126:127]
	v_pk_mul_f32 v[112:113], v[112:113], v[120:121]
	v_pk_add_f32 v[96:97], v[96:97], v[92:93]
	v_pk_mul_f32 v[106:107], v[90:91], v[106:107]
	v_pk_mul_f32 v[104:105], v[104:105], s[62:63] op_sel_hi:[1,0]
	v_pk_mul_f32 v[114:115], v[114:115], v[132:133]
	v_cvt_pk_bf16_f32 v112, v116, v112
	v_cvt_pk_bf16_f32 v113, v117, v113
	v_pk_add_f32 v[98:99], v[98:99], v[94:95]
	v_mul_f32_e32 v96, 0xbfb8aa3b, v96
	v_mul_f32_e32 v97, 0xbfb8aa3b, v97
	v_pk_mul_f32 v[106:107], v[106:107], s[62:63] op_sel_hi:[1,0]
	v_exp_f32_e32 v116, v104
	v_exp_f32_e32 v117, v105
	v_cvt_pk_bf16_f32 v114, v118, v114
	v_cvt_pk_bf16_f32 v115, v119, v115
	v_exp_f32_e32 v96, v96
	v_exp_f32_e32 v97, v97
	v_mul_f32_e32 v98, 0xbfb8aa3b, v98
	v_mul_f32_e32 v99, 0xbfb8aa3b, v99
	v_exp_f32_e32 v118, v106
	v_exp_f32_e32 v119, v107
	v_pk_add_f32 v[84:85], v[84:85], v[80:81]
	v_exp_f32_e32 v98, v98
	v_exp_f32_e32 v99, v99
	v_pk_add_f32 v[86:87], v[86:87], v[82:83]
	v_mul_f32_e32 v84, 0xbfb8aa3b, v84
	v_mul_f32_e32 v85, 0xbfb8aa3b, v85
	v_exp_f32_e32 v84, v84
	v_exp_f32_e32 v85, v85
	v_mul_f32_e32 v86, 0xbfb8aa3b, v86
	v_mul_f32_e32 v87, 0xbfb8aa3b, v87
	v_pk_mul_f32 v[116:117], v[116:117], v[116:117]
	v_exp_f32_e32 v86, v86
	v_exp_f32_e32 v87, v87
	v_add_f32_e32 v96, 1.0, v96
	v_add_f32_e32 v97, 1.0, v97
	v_pk_mul_f32 v[118:119], v[118:119], v[118:119]
	v_sub_f32_e32 v116, 1.0, v116
	v_sub_f32_e32 v117, 1.0, v117
	v_rcp_f32_e32 v96, v96
	v_rcp_f32_e32 v97, v97
	v_add_f32_e32 v98, 1.0, v98
	v_add_f32_e32 v99, 1.0, v99
	v_sqrt_f32_e32 v116, v116
	v_sub_f32_e32 v118, 1.0, v118
	v_sub_f32_e32 v119, 1.0, v119
	v_sqrt_f32_e32 v117, v117
	v_rcp_f32_e32 v98, v98
	v_rcp_f32_e32 v99, v99
	v_sqrt_f32_e32 v118, v118
	v_sqrt_f32_e32 v119, v119
	v_add_f32_e32 v84, 1.0, v84
	v_add_f32_e32 v85, 1.0, v85
	v_rcp_f32_e32 v84, v84
	v_rcp_f32_e32 v85, v85
	v_add_f32_e32 v86, 1.0, v86
	v_add_f32_e32 v87, 1.0, v87
	v_rcp_f32_e32 v86, v86
	v_rcp_f32_e32 v87, v87
	global_store_dwordx4 v[124:125], v[112:115], off offset:16
	v_pk_mul_f32 v[96:97], v[96:97], v[116:117]
	v_lshlrev_b32_e32 v120, 16, v165
	v_lshlrev_b32_e32 v114, 16, v164
	v_and_b32_e32 v115, 0xffff0000, v164
	v_lshlrev_b64 v[112:113], 13, v[206:207]
	v_and_b32_e32 v121, 0xffff0000, v165
	v_pk_mul_f32 v[98:99], v[98:99], v[118:119]
	v_pk_mul_f32 v[96:97], v[96:97], v[114:115]
	v_pk_mul_f32 v[98:99], v[98:99], v[120:121]
	v_cvt_pk_bf16_f32 v96, v104, v96
	v_cvt_pk_bf16_f32 v97, v105, v97
	v_lshl_add_u64 v[104:105], s[92:93], 0, v[112:113]
	v_pk_mul_f32 v[84:85], v[64:65], v[84:85]
	v_cvt_pk_bf16_f32 v98, v106, v98
	v_cvt_pk_bf16_f32 v99, v107, v99
	v_lshl_add_u64 v[104:105], v[104:105], 0, v[196:197]
	v_pk_add_f32 v[76:77], v[76:77], v[72:73]
	v_pk_mul_f32 v[86:87], v[66:67], v[86:87]
	v_pk_mul_f32 v[84:85], v[84:85], s[62:63] op_sel_hi:[1,0]
	v_pk_add_f32 v[60:61], v[60:61], v[100:101]
	global_store_dwordx4 v[104:105], v[96:99], off
	v_pk_add_f32 v[78:79], v[78:79], v[74:75]
	v_mul_f32_e32 v76, 0xbfb8aa3b, v76
	v_mul_f32_e32 v77, 0xbfb8aa3b, v77
	v_pk_mul_f32 v[86:87], v[86:87], s[62:63] op_sel_hi:[1,0]
	v_exp_f32_e32 v98, v84
	v_exp_f32_e32 v99, v85
	v_pk_add_f32 v[62:63], v[62:63], v[102:103]
	v_mul_f32_e32 v60, 0xbfb8aa3b, v60
	v_mul_f32_e32 v61, 0xbfb8aa3b, v61
	v_exp_f32_e32 v76, v76
	v_exp_f32_e32 v77, v77
	v_mul_f32_e32 v78, 0xbfb8aa3b, v78
	v_mul_f32_e32 v79, 0xbfb8aa3b, v79
	v_exp_f32_e32 v106, v86
	v_exp_f32_e32 v107, v87
	v_exp_f32_e32 v60, v60
	v_exp_f32_e32 v61, v61
	v_mul_f32_e32 v62, 0xbfb8aa3b, v62
	v_mul_f32_e32 v63, 0xbfb8aa3b, v63
	v_exp_f32_e32 v78, v78
	v_exp_f32_e32 v79, v79
	v_exp_f32_e32 v62, v62
	v_exp_f32_e32 v63, v63
	v_pk_mul_f32 v[98:99], v[98:99], v[98:99]
	v_add_f32_e32 v76, 1.0, v76
	v_add_f32_e32 v77, 1.0, v77
	v_pk_mul_f32 v[106:107], v[106:107], v[106:107]
	v_sub_f32_e32 v98, 1.0, v98
	v_sub_f32_e32 v99, 1.0, v99
	v_add_f32_e32 v60, 1.0, v60
	v_add_f32_e32 v61, 1.0, v61
	v_rcp_f32_e32 v76, v76
	v_rcp_f32_e32 v77, v77
	v_add_f32_e32 v78, 1.0, v78
	v_add_f32_e32 v79, 1.0, v79
	v_sqrt_f32_e32 v98, v98
	v_sub_f32_e32 v106, 1.0, v106
	v_sub_f32_e32 v107, 1.0, v107
	v_sqrt_f32_e32 v99, v99
	v_rcp_f32_e32 v60, v60
	v_rcp_f32_e32 v61, v61
	v_add_f32_e32 v62, 1.0, v62
	v_add_f32_e32 v63, 1.0, v63
	v_rcp_f32_e32 v78, v78
	v_rcp_f32_e32 v79, v79
	v_sqrt_f32_e32 v106, v106
	v_sqrt_f32_e32 v107, v107
	v_rcp_f32_e32 v62, v62
	v_rcp_f32_e32 v63, v63
	v_lshlrev_b32_e32 v96, 16, v166
	v_and_b32_e32 v97, 0xffff0000, v166
	v_pk_mul_f32 v[76:77], v[76:77], v[98:99]
	v_pk_mul_f32 v[60:61], v[88:89], v[60:61]
	v_lshlrev_b32_e32 v112, 16, v167
	v_and_b32_e32 v113, 0xffff0000, v167
	v_pk_mul_f32 v[78:79], v[78:79], v[106:107]
	v_pk_mul_f32 v[76:77], v[76:77], v[96:97]
	v_pk_add_f32 v[56:57], v[56:57], v[92:93]
	v_pk_mul_f32 v[62:63], v[90:91], v[62:63]
; __device__ __forceinline__ unsigned cvt_pk_bf16(float lo, float hi) { unsigned r; asm volatile("v_cvt_pk_bf16_f32 %0, %1, %2" : "=v"(r) : "v"(lo), "v"(hi)); return r; }
; __device__ __forceinline__ float bf_lo(unsigned w) { return __uint_as_float(w << 16); }
; __device__ __forceinline__ float bf_hi(unsigned w) { return __uint_as_float(w & 0xffff0000u); }
;     __device__ __forceinline__ void operator()(EPI_ARGS) const {
;     ...
;         for (int ai = 0; ai < 2; ++ai)
; #pragma unroll
;             for (int m = 0; m < 4; ++m) {
;                 const int row = ROW_OF(ai, m);
; #pragma unroll
;                 for (int n = 0; n < 2; ++n) {
;                     const unsigned w0 = n ? vv[ai][m].z : vv[ai][m].x, w1 = n ? vv[ai][m].w : vv[ai][m].y;
;                     const f32x4 vx = (f32x4){bf_lo(w0), bf_hi(w0), bf_lo(w1), bf_hi(w1)};
;                     const f32x4 r = sigmoid4(acc[ai][0][m][n] + ba[n]), ig = sigmoid4(acc[ai][1][m][n] + bi[n]);
;                     const f32x4 la = sp[n] * r * (-1.4426950409f);
;                     f32x4 av;
; #pragma unroll
;                     for (int j = 0; j < 4; ++j) av[j] = __builtin_amdgcn_exp2f(la[j]);
;                     const f32x4 om = 1.0f - av * av; f32x4 sq;
; #pragma unroll
;                     for (int j = 0; j < 4; ++j) sq[j] = __builtin_amdgcn_sqrtf(om[j]);
;                     const f32x4 bx = sq * ig * vx;
;                     u32x4 w; w.x = cvt_pk_bf16(la[0], bx[0]); w.y = cvt_pk_bf16(la[1], bx[1]); w.z = cvt_pk_bf16(la[2], bx[2]); w.w = cvt_pk_bf16(la[3], bx[3]);
;                     *(u32x4*)(AB + (size_t)row * LW + c0 + 4 * n) = w;
	v_pk_mul_f32 v[60:61], v[60:61], s[62:63] op_sel_hi:[1,0]
	v_pk_mul_f32 v[78:79], v[78:79], v[112:113]
	v_cvt_pk_bf16_f32 v76, v84, v76
	v_cvt_pk_bf16_f32 v77, v85, v77
	v_pk_add_f32 v[58:59], v[58:59], v[94:95]
	v_mul_f32_e32 v56, 0xbfb8aa3b, v56
	v_mul_f32_e32 v57, 0xbfb8aa3b, v57
	v_pk_mul_f32 v[62:63], v[62:63], s[62:63] op_sel_hi:[1,0]
	v_exp_f32_e32 v84, v60
	v_exp_f32_e32 v85, v61
	v_cvt_pk_bf16_f32 v78, v86, v78
	v_cvt_pk_bf16_f32 v79, v87, v79
	v_exp_f32_e32 v56, v56
	v_exp_f32_e32 v57, v57
	v_mul_f32_e32 v58, 0xbfb8aa3b, v58
	v_mul_f32_e32 v59, 0xbfb8aa3b, v59
	v_exp_f32_e32 v86, v62
	v_exp_f32_e32 v87, v63
	v_pk_add_f32 v[52:53], v[52:53], v[80:81]
	v_exp_f32_e32 v58, v58
	v_exp_f32_e32 v59, v59
	v_pk_add_f32 v[54:55], v[54:55], v[82:83]
	v_mul_f32_e32 v52, 0xbfb8aa3b, v52
	v_mul_f32_e32 v53, 0xbfb8aa3b, v53
	v_exp_f32_e32 v52, v52
	v_exp_f32_e32 v53, v53
	v_mul_f32_e32 v54, 0xbfb8aa3b, v54
	v_mul_f32_e32 v55, 0xbfb8aa3b, v55
	v_pk_mul_f32 v[84:85], v[84:85], v[84:85]
	v_exp_f32_e32 v54, v54
	v_exp_f32_e32 v55, v55
	v_add_f32_e32 v56, 1.0, v56
	v_add_f32_e32 v57, 1.0, v57
	v_pk_mul_f32 v[86:87], v[86:87], v[86:87]
	v_sub_f32_e32 v84, 1.0, v84
	v_sub_f32_e32 v85, 1.0, v85
	v_rcp_f32_e32 v56, v56
	v_rcp_f32_e32 v57, v57
	v_add_f32_e32 v58, 1.0, v58
	v_add_f32_e32 v59, 1.0, v59
	v_sqrt_f32_e32 v84, v84
	v_sub_f32_e32 v86, 1.0, v86
	v_sub_f32_e32 v87, 1.0, v87
	v_sqrt_f32_e32 v85, v85
	v_rcp_f32_e32 v58, v58
	v_rcp_f32_e32 v59, v59
	v_sqrt_f32_e32 v86, v86
	v_sqrt_f32_e32 v87, v87
	v_add_f32_e32 v52, 1.0, v52
	v_add_f32_e32 v53, 1.0, v53
	v_rcp_f32_e32 v52, v52
	v_rcp_f32_e32 v53, v53
	v_add_f32_e32 v54, 1.0, v54
	v_add_f32_e32 v55, 1.0, v55
	v_rcp_f32_e32 v54, v54
	v_rcp_f32_e32 v55, v55
	global_store_dwordx4 v[104:105], v[76:79], off offset:16
	v_pk_mul_f32 v[56:57], v[56:57], v[84:85]
	v_lshlrev_b32_e32 v96, 16, v149
	v_lshlrev_b32_e32 v78, 16, v148
	v_and_b32_e32 v79, 0xffff0000, v148
	v_lshlrev_b64 v[76:77], 13, v[204:205]
	v_and_b32_e32 v97, 0xffff0000, v149
	v_pk_mul_f32 v[58:59], v[58:59], v[86:87]
	v_pk_mul_f32 v[56:57], v[56:57], v[78:79]
	v_pk_mul_f32 v[58:59], v[58:59], v[96:97]
	v_cvt_pk_bf16_f32 v56, v60, v56
	v_cvt_pk_bf16_f32 v57, v61, v57
	v_lshl_add_u64 v[60:61], s[92:93], 0, v[76:77]
	v_pk_mul_f32 v[52:53], v[64:65], v[52:53]
	v_cvt_pk_bf16_f32 v58, v62, v58
	v_cvt_pk_bf16_f32 v59, v63, v59
	v_lshl_add_u64 v[60:61], v[60:61], 0, v[196:197]
	v_pk_add_f32 v[48:49], v[48:49], v[72:73]
	v_pk_mul_f32 v[54:55], v[66:67], v[54:55]
	v_pk_mul_f32 v[52:53], v[52:53], s[62:63] op_sel_hi:[1,0]
	v_pk_add_f32 v[44:45], v[44:45], v[100:101]
	global_store_dwordx4 v[60:61], v[56:59], off
	v_pk_add_f32 v[50:51], v[50:51], v[74:75]
	v_mul_f32_e32 v48, 0xbfb8aa3b, v48
	v_mul_f32_e32 v49, 0xbfb8aa3b, v49
	v_pk_mul_f32 v[54:55], v[54:55], s[62:63] op_sel_hi:[1,0]
	v_exp_f32_e32 v58, v52
	v_exp_f32_e32 v59, v53
	v_pk_add_f32 v[46:47], v[46:47], v[102:103]
	v_mul_f32_e32 v44, 0xbfb8aa3b, v44
	v_mul_f32_e32 v45, 0xbfb8aa3b, v45
	v_exp_f32_e32 v48, v48
	v_exp_f32_e32 v49, v49
	v_mul_f32_e32 v50, 0xbfb8aa3b, v50
	v_mul_f32_e32 v51, 0xbfb8aa3b, v51
	v_exp_f32_e32 v62, v54
	v_exp_f32_e32 v63, v55
	v_exp_f32_e32 v44, v44
	v_exp_f32_e32 v45, v45
	v_mul_f32_e32 v46, 0xbfb8aa3b, v46
	v_mul_f32_e32 v47, 0xbfb8aa3b, v47
	v_exp_f32_e32 v50, v50
	v_exp_f32_e32 v51, v51
	v_exp_f32_e32 v46, v46
	v_exp_f32_e32 v47, v47
	v_pk_mul_f32 v[58:59], v[58:59], v[58:59]
	v_add_f32_e32 v48, 1.0, v48
	v_add_f32_e32 v49, 1.0, v49
	v_pk_mul_f32 v[62:63], v[62:63], v[62:63]
	v_sub_f32_e32 v58, 1.0, v58
	v_sub_f32_e32 v59, 1.0, v59
	v_add_f32_e32 v44, 1.0, v44
	v_add_f32_e32 v45, 1.0, v45
	v_rcp_f32_e32 v48, v48
	v_rcp_f32_e32 v49, v49
	v_add_f32_e32 v50, 1.0, v50
	v_add_f32_e32 v51, 1.0, v51
	v_sqrt_f32_e32 v58, v58
	v_sub_f32_e32 v62, 1.0, v62
	v_sub_f32_e32 v63, 1.0, v63
	v_sqrt_f32_e32 v59, v59
	v_rcp_f32_e32 v44, v44
	v_rcp_f32_e32 v45, v45
	v_add_f32_e32 v46, 1.0, v46
	v_add_f32_e32 v47, 1.0, v47
	v_rcp_f32_e32 v50, v50
	v_rcp_f32_e32 v51, v51
	v_sqrt_f32_e32 v62, v62
	v_sqrt_f32_e32 v63, v63
	v_rcp_f32_e32 v46, v46
	v_rcp_f32_e32 v47, v47
	v_lshlrev_b32_e32 v56, 16, v150
	v_and_b32_e32 v57, 0xffff0000, v150
	v_pk_mul_f32 v[48:49], v[48:49], v[58:59]
	v_pk_mul_f32 v[44:45], v[88:89], v[44:45]
	v_lshlrev_b32_e32 v76, 16, v151
	v_and_b32_e32 v77, 0xffff0000, v151
	v_pk_mul_f32 v[50:51], v[50:51], v[62:63]
	v_pk_mul_f32 v[48:49], v[48:49], v[56:57]
	v_pk_add_f32 v[40:41], v[40:41], v[92:93]
	v_pk_mul_f32 v[46:47], v[90:91], v[46:47]
	v_pk_mul_f32 v[44:45], v[44:45], s[62:63] op_sel_hi:[1,0]
	v_pk_mul_f32 v[50:51], v[50:51], v[76:77]
	v_cvt_pk_bf16_f32 v48, v52, v48
	v_cvt_pk_bf16_f32 v49, v53, v49
	v_pk_add_f32 v[42:43], v[42:43], v[94:95]
	v_mul_f32_e32 v40, 0xbfb8aa3b, v40
	v_mul_f32_e32 v41, 0xbfb8aa3b, v41
	v_pk_mul_f32 v[46:47], v[46:47], s[62:63] op_sel_hi:[1,0]
	v_exp_f32_e32 v52, v44
	v_exp_f32_e32 v53, v45
	v_cvt_pk_bf16_f32 v50, v54, v50
	v_cvt_pk_bf16_f32 v51, v55, v51
	v_exp_f32_e32 v40, v40
	v_exp_f32_e32 v41, v41
	v_mul_f32_e32 v42, 0xbfb8aa3b, v42
	v_mul_f32_e32 v43, 0xbfb8aa3b, v43
	v_exp_f32_e32 v54, v46
	v_exp_f32_e32 v55, v47
	v_pk_add_f32 v[36:37], v[36:37], v[80:81]
	v_exp_f32_e32 v42, v42
	v_exp_f32_e32 v43, v43
	v_pk_add_f32 v[38:39], v[38:39], v[82:83]
	v_mul_f32_e32 v36, 0xbfb8aa3b, v36
	v_mul_f32_e32 v37, 0xbfb8aa3b, v37
	v_exp_f32_e32 v36, v36
	v_exp_f32_e32 v37, v37
	v_mul_f32_e32 v38, 0xbfb8aa3b, v38
	v_mul_f32_e32 v39, 0xbfb8aa3b, v39
	v_pk_mul_f32 v[52:53], v[52:53], v[52:53]
	v_exp_f32_e32 v38, v38
	v_exp_f32_e32 v39, v39
	v_add_f32_e32 v40, 1.0, v40
	v_add_f32_e32 v41, 1.0, v41
	v_pk_mul_f32 v[54:55], v[54:55], v[54:55]
; __device__ __forceinline__ unsigned cvt_pk_bf16(float lo, float hi) { unsigned r; asm volatile("v_cvt_pk_bf16_f32 %0, %1, %2" : "=v"(r) : "v"(lo), "v"(hi)); return r; }
; __device__ __forceinline__ float bf_lo(unsigned w) { return __uint_as_float(w << 16); }
; __device__ __forceinline__ float bf_hi(unsigned w) { return __uint_as_float(w & 0xffff0000u); }
;     __device__ __forceinline__ void operator()(EPI_ARGS) const {
;     ...
;         for (int ai = 0; ai < 2; ++ai)
; #pragma unroll
;             for (int m = 0; m < 4; ++m) {
;                 const int row = ROW_OF(ai, m);
; #pragma unroll
;                 for (int n = 0; n < 2; ++n) {
;                     const unsigned w0 = n ? vv[ai][m].z : vv[ai][m].x, w1 = n ? vv[ai][m].w : vv[ai][m].y;
;                     const f32x4 vx = (f32x4){bf_lo(w0), bf_hi(w0), bf_lo(w1), bf_hi(w1)};
;                     const f32x4 r = sigmoid4(acc[ai][0][m][n] + ba[n]), ig = sigmoid4(acc[ai][1][m][n] + bi[n]);
;                     const f32x4 la = sp[n] * r * (-1.4426950409f);
;                     f32x4 av;
; #pragma unroll
;                     for (int j = 0; j < 4; ++j) av[j] = __builtin_amdgcn_exp2f(la[j]);
;                     const f32x4 om = 1.0f - av * av; f32x4 sq;
; #pragma unroll
;                     for (int j = 0; j < 4; ++j) sq[j] = __builtin_amdgcn_sqrtf(om[j]);
;                     const f32x4 bx = sq * ig * vx;
;                     u32x4 w; w.x = cvt_pk_bf16(la[0], bx[0]); w.y = cvt_pk_bf16(la[1], bx[1]); w.z = cvt_pk_bf16(la[2], bx[2]); w.w = cvt_pk_bf16(la[3], bx[3]);
;                     *(u32x4*)(AB + (size_t)row * LW + c0 + 4 * n) = w;
	v_sub_f32_e32 v52, 1.0, v52
	v_sub_f32_e32 v53, 1.0, v53
	v_rcp_f32_e32 v40, v40
	v_rcp_f32_e32 v41, v41
	v_add_f32_e32 v42, 1.0, v42
	v_add_f32_e32 v43, 1.0, v43
	v_sqrt_f32_e32 v52, v52
	v_sub_f32_e32 v54, 1.0, v54
	v_sub_f32_e32 v55, 1.0, v55
	v_sqrt_f32_e32 v53, v53
	v_rcp_f32_e32 v42, v42
	v_rcp_f32_e32 v43, v43
	v_sqrt_f32_e32 v54, v54
	v_sqrt_f32_e32 v55, v55
	v_add_f32_e32 v36, 1.0, v36
	v_add_f32_e32 v37, 1.0, v37
	v_rcp_f32_e32 v36, v36
	v_rcp_f32_e32 v37, v37
	v_add_f32_e32 v38, 1.0, v38
	v_add_f32_e32 v39, 1.0, v39
	v_rcp_f32_e32 v38, v38
	v_rcp_f32_e32 v39, v39
	global_store_dwordx4 v[60:61], v[48:51], off offset:16
	v_pk_mul_f32 v[40:41], v[40:41], v[52:53]
	v_lshlrev_b32_e32 v56, 16, v129
	v_lshlrev_b32_e32 v50, 16, v128
	v_and_b32_e32 v51, 0xffff0000, v128
	v_lshlrev_b64 v[48:49], 13, v[202:203]
	v_and_b32_e32 v57, 0xffff0000, v129
	v_pk_mul_f32 v[42:43], v[42:43], v[54:55]
	v_pk_mul_f32 v[40:41], v[40:41], v[50:51]
	v_pk_mul_f32 v[42:43], v[42:43], v[56:57]
	v_cvt_pk_bf16_f32 v40, v44, v40
	v_cvt_pk_bf16_f32 v41, v45, v41
	v_lshl_add_u64 v[44:45], s[92:93], 0, v[48:49]
	v_pk_mul_f32 v[36:37], v[64:65], v[36:37]
	v_cvt_pk_bf16_f32 v42, v46, v42
	v_cvt_pk_bf16_f32 v43, v47, v43
	v_lshl_add_u64 v[44:45], v[44:45], 0, v[196:197]
	v_pk_add_f32 v[32:33], v[32:33], v[72:73]
	v_pk_mul_f32 v[38:39], v[66:67], v[38:39]
	v_pk_mul_f32 v[36:37], v[36:37], s[62:63] op_sel_hi:[1,0]
	v_pk_add_f32 v[28:29], v[28:29], v[100:101]
	global_store_dwordx4 v[44:45], v[40:43], off
	v_pk_add_f32 v[34:35], v[34:35], v[74:75]
	v_mul_f32_e32 v32, 0xbfb8aa3b, v32
	v_mul_f32_e32 v33, 0xbfb8aa3b, v33
	v_pk_mul_f32 v[38:39], v[38:39], s[62:63] op_sel_hi:[1,0]
	v_exp_f32_e32 v42, v36
	v_exp_f32_e32 v43, v37
	v_pk_add_f32 v[30:31], v[30:31], v[102:103]
	v_mul_f32_e32 v28, 0xbfb8aa3b, v28
	v_mul_f32_e32 v29, 0xbfb8aa3b, v29
	v_exp_f32_e32 v32, v32
	v_exp_f32_e32 v33, v33
	v_mul_f32_e32 v34, 0xbfb8aa3b, v34
	v_mul_f32_e32 v35, 0xbfb8aa3b, v35
	v_exp_f32_e32 v46, v38
	v_exp_f32_e32 v47, v39
	v_exp_f32_e32 v28, v28
	v_exp_f32_e32 v29, v29
	v_mul_f32_e32 v30, 0xbfb8aa3b, v30
	v_mul_f32_e32 v31, 0xbfb8aa3b, v31
	v_exp_f32_e32 v34, v34
	v_exp_f32_e32 v35, v35
	v_exp_f32_e32 v30, v30
	v_exp_f32_e32 v31, v31
	v_pk_mul_f32 v[42:43], v[42:43], v[42:43]
	v_add_f32_e32 v32, 1.0, v32
	v_add_f32_e32 v33, 1.0, v33
	v_pk_mul_f32 v[46:47], v[46:47], v[46:47]
	v_sub_f32_e32 v42, 1.0, v42
	v_sub_f32_e32 v43, 1.0, v43
	v_add_f32_e32 v28, 1.0, v28
	v_add_f32_e32 v29, 1.0, v29
	v_rcp_f32_e32 v32, v32
	v_rcp_f32_e32 v33, v33
	v_add_f32_e32 v34, 1.0, v34
	v_add_f32_e32 v35, 1.0, v35
	v_sqrt_f32_e32 v42, v42
	v_sub_f32_e32 v46, 1.0, v46
	v_sub_f32_e32 v47, 1.0, v47
	v_sqrt_f32_e32 v43, v43
	v_rcp_f32_e32 v28, v28
	v_rcp_f32_e32 v29, v29
	v_add_f32_e32 v30, 1.0, v30
	v_add_f32_e32 v31, 1.0, v31
	v_rcp_f32_e32 v34, v34
	v_rcp_f32_e32 v35, v35
	v_sqrt_f32_e32 v46, v46
	v_sqrt_f32_e32 v47, v47
	v_rcp_f32_e32 v30, v30
	v_rcp_f32_e32 v31, v31
	v_lshlrev_b32_e32 v40, 16, v130
	v_and_b32_e32 v41, 0xffff0000, v130
	v_pk_mul_f32 v[32:33], v[32:33], v[42:43]
	v_pk_mul_f32 v[28:29], v[88:89], v[28:29]
	v_lshlrev_b32_e32 v48, 16, v131
	v_and_b32_e32 v49, 0xffff0000, v131
	v_pk_mul_f32 v[34:35], v[34:35], v[46:47]
	v_pk_mul_f32 v[32:33], v[32:33], v[40:41]
	v_pk_add_f32 v[24:25], v[24:25], v[92:93]
	v_pk_mul_f32 v[30:31], v[90:91], v[30:31]
	v_pk_mul_f32 v[28:29], v[28:29], s[62:63] op_sel_hi:[1,0]
	v_pk_mul_f32 v[34:35], v[34:35], v[48:49]
	v_cvt_pk_bf16_f32 v32, v36, v32
	v_cvt_pk_bf16_f32 v33, v37, v33
	v_pk_add_f32 v[26:27], v[26:27], v[94:95]
	v_mul_f32_e32 v24, 0xbfb8aa3b, v24
	v_mul_f32_e32 v25, 0xbfb8aa3b, v25
	v_pk_mul_f32 v[30:31], v[30:31], s[62:63] op_sel_hi:[1,0]
	v_exp_f32_e32 v36, v28
	v_exp_f32_e32 v37, v29
	v_cvt_pk_bf16_f32 v34, v38, v34
	v_cvt_pk_bf16_f32 v35, v39, v35
	v_exp_f32_e32 v24, v24
	v_exp_f32_e32 v25, v25
	v_mul_f32_e32 v26, 0xbfb8aa3b, v26
	v_mul_f32_e32 v27, 0xbfb8aa3b, v27
	v_exp_f32_e32 v38, v30
	v_exp_f32_e32 v39, v31
	v_pk_add_f32 v[20:21], v[20:21], v[80:81]
	v_exp_f32_e32 v26, v26
	v_exp_f32_e32 v27, v27
	v_pk_add_f32 v[22:23], v[22:23], v[82:83]
	v_mul_f32_e32 v20, 0xbfb8aa3b, v20
	v_mul_f32_e32 v21, 0xbfb8aa3b, v21
	v_exp_f32_e32 v20, v20
	v_exp_f32_e32 v21, v21
	v_mul_f32_e32 v22, 0xbfb8aa3b, v22
	v_mul_f32_e32 v23, 0xbfb8aa3b, v23
	v_pk_mul_f32 v[36:37], v[36:37], v[36:37]
	v_exp_f32_e32 v22, v22
	v_exp_f32_e32 v23, v23
	v_add_f32_e32 v24, 1.0, v24
	v_add_f32_e32 v25, 1.0, v25
	v_pk_mul_f32 v[38:39], v[38:39], v[38:39]
	v_sub_f32_e32 v36, 1.0, v36
	v_sub_f32_e32 v37, 1.0, v37
	v_rcp_f32_e32 v24, v24
	v_rcp_f32_e32 v25, v25
	v_add_f32_e32 v26, 1.0, v26
	v_add_f32_e32 v27, 1.0, v27
	v_sqrt_f32_e32 v36, v36
	v_sub_f32_e32 v38, 1.0, v38
	v_sub_f32_e32 v39, 1.0, v39
	v_sqrt_f32_e32 v37, v37
	v_rcp_f32_e32 v26, v26
	v_rcp_f32_e32 v27, v27
	v_sqrt_f32_e32 v38, v38
	v_sqrt_f32_e32 v39, v39
	v_add_f32_e32 v20, 1.0, v20
	v_add_f32_e32 v21, 1.0, v21
	v_rcp_f32_e32 v20, v20
	v_rcp_f32_e32 v21, v21
	v_add_f32_e32 v22, 1.0, v22
	v_add_f32_e32 v23, 1.0, v23
	v_rcp_f32_e32 v22, v22
	v_rcp_f32_e32 v23, v23
	global_store_dwordx4 v[44:45], v[32:35], off offset:16
	v_pk_mul_f32 v[24:25], v[24:25], v[36:37]
	v_lshlrev_b32_e32 v40, 16, v109
	v_lshlrev_b32_e32 v34, 16, v108
	v_and_b32_e32 v35, 0xffff0000, v108
	v_lshlrev_b64 v[32:33], 13, v[200:201]
	v_and_b32_e32 v41, 0xffff0000, v109
	v_pk_mul_f32 v[26:27], v[26:27], v[38:39]
	v_pk_mul_f32 v[24:25], v[24:25], v[34:35]
	v_pk_mul_f32 v[26:27], v[26:27], v[40:41]
	v_cvt_pk_bf16_f32 v24, v28, v24
	v_cvt_pk_bf16_f32 v25, v29, v25
	v_lshl_add_u64 v[28:29], s[92:93], 0, v[32:33]
	v_pk_mul_f32 v[20:21], v[64:65], v[20:21]
; __device__ __forceinline__ unsigned cvt_pk_bf16(float lo, float hi) { unsigned r; asm volatile("v_cvt_pk_bf16_f32 %0, %1, %2" : "=v"(r) : "v"(lo), "v"(hi)); return r; }
; __device__ __forceinline__ float bf_lo(unsigned w) { return __uint_as_float(w << 16); }
; __device__ __forceinline__ float bf_hi(unsigned w) { return __uint_as_float(w & 0xffff0000u); }
;     __device__ __forceinline__ void operator()(EPI_ARGS) const {
;     ...
;         for (int ai = 0; ai < 2; ++ai)
; #pragma unroll
;             for (int m = 0; m < 4; ++m) {
;                 const int row = ROW_OF(ai, m);
; #pragma unroll
;                 for (int n = 0; n < 2; ++n) {
;                     const unsigned w0 = n ? vv[ai][m].z : vv[ai][m].x, w1 = n ? vv[ai][m].w : vv[ai][m].y;
;                     const f32x4 vx = (f32x4){bf_lo(w0), bf_hi(w0), bf_lo(w1), bf_hi(w1)};
;                     const f32x4 r = sigmoid4(acc[ai][0][m][n] + ba[n]), ig = sigmoid4(acc[ai][1][m][n] + bi[n]);
;                     const f32x4 la = sp[n] * r * (-1.4426950409f);
;                     f32x4 av;
; #pragma unroll
;                     for (int j = 0; j < 4; ++j) av[j] = __builtin_amdgcn_exp2f(la[j]);
;                     const f32x4 om = 1.0f - av * av; f32x4 sq;
; #pragma unroll
;                     for (int j = 0; j < 4; ++j) sq[j] = __builtin_amdgcn_sqrtf(om[j]);
;                     const f32x4 bx = sq * ig * vx;
;                     u32x4 w; w.x = cvt_pk_bf16(la[0], bx[0]); w.y = cvt_pk_bf16(la[1], bx[1]); w.z = cvt_pk_bf16(la[2], bx[2]); w.w = cvt_pk_bf16(la[3], bx[3]);
;                     *(u32x4*)(AB + (size_t)row * LW + c0 + 4 * n) = w;
	v_cvt_pk_bf16_f32 v26, v30, v26
	v_cvt_pk_bf16_f32 v27, v31, v27
	v_lshl_add_u64 v[28:29], v[28:29], 0, v[196:197]
	v_pk_add_f32 v[16:17], v[16:17], v[72:73]
	v_pk_mul_f32 v[22:23], v[66:67], v[22:23]
	v_pk_mul_f32 v[20:21], v[20:21], s[62:63] op_sel_hi:[1,0]
	v_pk_add_f32 v[12:13], v[12:13], v[100:101]
	global_store_dwordx4 v[28:29], v[24:27], off
	v_pk_add_f32 v[18:19], v[18:19], v[74:75]
	v_mul_f32_e32 v16, 0xbfb8aa3b, v16
	v_mul_f32_e32 v17, 0xbfb8aa3b, v17
	v_pk_mul_f32 v[22:23], v[22:23], s[62:63] op_sel_hi:[1,0]
	v_exp_f32_e32 v26, v20
	v_exp_f32_e32 v27, v21
	v_pk_add_f32 v[14:15], v[14:15], v[102:103]
	v_mul_f32_e32 v12, 0xbfb8aa3b, v12
	v_mul_f32_e32 v13, 0xbfb8aa3b, v13
	v_exp_f32_e32 v16, v16
	v_exp_f32_e32 v17, v17
	v_mul_f32_e32 v18, 0xbfb8aa3b, v18
	v_mul_f32_e32 v19, 0xbfb8aa3b, v19
	v_exp_f32_e32 v30, v22
	v_exp_f32_e32 v31, v23
	v_exp_f32_e32 v12, v12
	v_exp_f32_e32 v13, v13
	v_mul_f32_e32 v14, 0xbfb8aa3b, v14
	v_mul_f32_e32 v15, 0xbfb8aa3b, v15
	v_exp_f32_e32 v18, v18
	v_exp_f32_e32 v19, v19
	v_exp_f32_e32 v14, v14
	v_exp_f32_e32 v15, v15
	v_pk_mul_f32 v[26:27], v[26:27], v[26:27]
	v_add_f32_e32 v16, 1.0, v16
	v_add_f32_e32 v17, 1.0, v17
	v_pk_mul_f32 v[30:31], v[30:31], v[30:31]
	v_sub_f32_e32 v26, 1.0, v26
	v_sub_f32_e32 v27, 1.0, v27
	v_add_f32_e32 v12, 1.0, v12
	v_add_f32_e32 v13, 1.0, v13
	v_rcp_f32_e32 v16, v16
	v_rcp_f32_e32 v17, v17
	v_add_f32_e32 v18, 1.0, v18
	v_add_f32_e32 v19, 1.0, v19
	v_sqrt_f32_e32 v26, v26
	v_sub_f32_e32 v30, 1.0, v30
	v_sub_f32_e32 v31, 1.0, v31
	v_sqrt_f32_e32 v27, v27
	v_rcp_f32_e32 v12, v12
	v_rcp_f32_e32 v13, v13
	v_add_f32_e32 v14, 1.0, v14
	v_add_f32_e32 v15, 1.0, v15
	v_rcp_f32_e32 v18, v18
	v_rcp_f32_e32 v19, v19
	v_sqrt_f32_e32 v30, v30
	v_sqrt_f32_e32 v31, v31
	v_rcp_f32_e32 v14, v14
	v_rcp_f32_e32 v15, v15
	v_lshlrev_b32_e32 v24, 16, v110
	v_and_b32_e32 v25, 0xffff0000, v110
	v_pk_mul_f32 v[16:17], v[16:17], v[26:27]
	v_pk_mul_f32 v[12:13], v[88:89], v[12:13]
	v_lshlrev_b32_e32 v32, 16, v111
	v_and_b32_e32 v33, 0xffff0000, v111
	v_pk_mul_f32 v[18:19], v[18:19], v[30:31]
	v_pk_mul_f32 v[16:17], v[16:17], v[24:25]
	v_pk_add_f32 v[8:9], v[8:9], v[92:93]
	v_pk_mul_f32 v[14:15], v[90:91], v[14:15]
	v_pk_mul_f32 v[12:13], v[12:13], s[62:63] op_sel_hi:[1,0]
	v_pk_mul_f32 v[18:19], v[18:19], v[32:33]
	v_cvt_pk_bf16_f32 v16, v20, v16
	v_cvt_pk_bf16_f32 v17, v21, v17
	v_pk_add_f32 v[10:11], v[10:11], v[94:95]
	v_mul_f32_e32 v8, 0xbfb8aa3b, v8
	v_mul_f32_e32 v9, 0xbfb8aa3b, v9
	v_pk_mul_f32 v[14:15], v[14:15], s[62:63] op_sel_hi:[1,0]
	v_exp_f32_e32 v20, v12
	v_exp_f32_e32 v21, v13
	v_cvt_pk_bf16_f32 v18, v22, v18
	v_cvt_pk_bf16_f32 v19, v23, v19
	v_exp_f32_e32 v8, v8
	v_exp_f32_e32 v9, v9
	v_mul_f32_e32 v10, 0xbfb8aa3b, v10
	v_mul_f32_e32 v11, 0xbfb8aa3b, v11
	v_exp_f32_e32 v22, v14
	v_exp_f32_e32 v23, v15
	v_pk_add_f32 v[6:7], v[6:7], v[82:83]
	v_pk_add_f32 v[4:5], v[4:5], v[80:81]
	v_exp_f32_e32 v10, v10
	v_exp_f32_e32 v11, v11
	v_mul_f32_e32 v4, 0xbfb8aa3b, v4
	v_mul_f32_e32 v5, 0xbfb8aa3b, v5
	v_mul_f32_e32 v6, 0xbfb8aa3b, v6
	v_mul_f32_e32 v7, 0xbfb8aa3b, v7
	v_exp_f32_e32 v4, v4
	v_exp_f32_e32 v5, v5
	v_exp_f32_e32 v6, v6
	v_exp_f32_e32 v7, v7
	v_pk_mul_f32 v[20:21], v[20:21], v[20:21]
	v_add_f32_e32 v8, 1.0, v8
	v_add_f32_e32 v9, 1.0, v9
	v_pk_mul_f32 v[22:23], v[22:23], v[22:23]
	v_sub_f32_e32 v20, 1.0, v20
	v_sub_f32_e32 v21, 1.0, v21
	v_rcp_f32_e32 v8, v8
	v_rcp_f32_e32 v9, v9
	v_add_f32_e32 v10, 1.0, v10
	v_add_f32_e32 v11, 1.0, v11
	v_sqrt_f32_e32 v20, v20
	v_sub_f32_e32 v22, 1.0, v22
	v_sub_f32_e32 v23, 1.0, v23
	v_sqrt_f32_e32 v21, v21
	v_rcp_f32_e32 v10, v10
	v_rcp_f32_e32 v11, v11
	v_sqrt_f32_e32 v22, v22
	v_sqrt_f32_e32 v23, v23
	v_add_f32_e32 v4, 1.0, v4
	v_add_f32_e32 v5, 1.0, v5
	v_add_f32_e32 v6, 1.0, v6
	v_add_f32_e32 v7, 1.0, v7
	v_rcp_f32_e32 v4, v4
	v_rcp_f32_e32 v5, v5
	v_rcp_f32_e32 v6, v6
	v_rcp_f32_e32 v7, v7
	global_store_dwordx4 v[28:29], v[16:19], off offset:16
	v_pk_mul_f32 v[8:9], v[8:9], v[20:21]
	v_lshlrev_b32_e32 v24, 16, v69
	v_lshlrev_b32_e32 v18, 16, v68
	v_and_b32_e32 v19, 0xffff0000, v68
	v_lshlrev_b64 v[16:17], 13, v[198:199]
	v_and_b32_e32 v25, 0xffff0000, v69
	v_pk_mul_f32 v[10:11], v[10:11], v[22:23]
	v_pk_mul_f32 v[8:9], v[8:9], v[18:19]
	v_pk_mul_f32 v[10:11], v[10:11], v[24:25]
	v_cvt_pk_bf16_f32 v8, v12, v8
	v_cvt_pk_bf16_f32 v9, v13, v9
	v_lshl_add_u64 v[12:13], s[92:93], 0, v[16:17]
	v_pk_mul_f32 v[6:7], v[66:67], v[6:7]
	v_pk_mul_f32 v[4:5], v[64:65], v[4:5]
	v_cvt_pk_bf16_f32 v10, v14, v10
	v_cvt_pk_bf16_f32 v11, v15, v11
	v_lshl_add_u64 v[12:13], v[12:13], 0, v[196:197]
	v_pk_add_f32 v[2:3], v[2:3], v[74:75]
	v_pk_add_f32 v[0:1], v[0:1], v[72:73]
	v_pk_mul_f32 v[6:7], v[6:7], s[62:63] op_sel_hi:[1,0]
	v_pk_mul_f32 v[4:5], v[4:5], s[62:63] op_sel_hi:[1,0]
	global_store_dwordx4 v[12:13], v[8:11], off
	v_mul_f32_e32 v0, 0xbfb8aa3b, v0
	v_mul_f32_e32 v1, 0xbfb8aa3b, v1
	v_mul_f32_e32 v2, 0xbfb8aa3b, v2
	v_mul_f32_e32 v3, 0xbfb8aa3b, v3
	v_exp_f32_e32 v10, v4
	v_exp_f32_e32 v14, v6
	v_exp_f32_e32 v15, v7
	v_exp_f32_e32 v11, v5
	v_exp_f32_e32 v0, v0
	v_exp_f32_e32 v1, v1
	v_exp_f32_e32 v2, v2
	v_exp_f32_e32 v3, v3
	v_pk_mul_f32 v[14:15], v[14:15], v[14:15]
	v_pk_mul_f32 v[10:11], v[10:11], v[10:11]
	v_add_f32_e32 v0, 1.0, v0
	v_add_f32_e32 v1, 1.0, v1
	v_add_f32_e32 v2, 1.0, v2
	v_add_f32_e32 v3, 1.0, v3
	v_sub_f32_e32 v10, 1.0, v10
	v_sub_f32_e32 v11, 1.0, v11
	v_sub_f32_e32 v14, 1.0, v14
	v_sub_f32_e32 v15, 1.0, v15
	v_rcp_f32_e32 v0, v0
	v_rcp_f32_e32 v1, v1
	v_rcp_f32_e32 v2, v2
	v_rcp_f32_e32 v3, v3
	v_sqrt_f32_e32 v10, v10
	v_sqrt_f32_e32 v14, v14
	v_sqrt_f32_e32 v15, v15
	v_sqrt_f32_e32 v11, v11
	v_lshlrev_b32_e32 v8, 16, v70
	v_and_b32_e32 v9, 0xffff0000, v70
	v_lshlrev_b32_e32 v16, 16, v71
	v_and_b32_e32 v17, 0xffff0000, v71
	v_pk_mul_f32 v[2:3], v[2:3], v[14:15]
	v_pk_mul_f32 v[0:1], v[0:1], v[10:11]
	v_pk_mul_f32 v[2:3], v[2:3], v[16:17]
	v_pk_mul_f32 v[0:1], v[0:1], v[8:9]
	s_nop 0
	v_cvt_pk_bf16_f32 v0, v4, v0
	v_cvt_pk_bf16_f32 v1, v5, v1
	v_cvt_pk_bf16_f32 v2, v6, v2
	v_cvt_pk_bf16_f32 v3, v7, v3
	global_store_dwordx4 v[12:13], v[0:3], off offset:16
	s_mov_b64 s[4:5], vcc
	s_waitcnt vmcnt(0)
	s_barrier
; __device__ __forceinline__ float bf_lo(unsigned w) { return __uint_as_float(w << 16); }
; __device__ __forceinline__ float bf_hi(unsigned w) { return __uint_as_float(w & 0xffff0000u); }
; __global__ void __launch_bounds__(NTHR, 2) hybrid_block_fwd(Args a) {
;     ...
;         const u32x2* pab = (const u32x2*)((const unsigned*)AF + r0 * LW) + c2;
;         f32x2 P = (f32x2){1.f, 1.f}, H = (f32x2){0.f, 0.f};
; #pragma unroll 32
;         for (int i = 0; i < CH_L; ++i) { const u32x2 q = pab[(size_t)i * (LW / 2)];
;             const f32x2 av = (f32x2){__builtin_amdgcn_exp2f(bf_lo(q.x)), __builtin_amdgcn_exp2f(bf_lo(q.y))}, bv = (f32x2){bf_hi(q.x), bf_hi(q.y)}; P = P * av; H = av * H + bv; }
	v_cmp_gt_u32_e32 vcc, 0x100, v212
	s_and_saveexec_b64 s[22:23], vcc
	s_cbranch_execz .Lp2b_agg_skip
	v_lshrrev_b32_e32 v1, 7, v212
	v_and_b32_e32 v2, 0x7f, v212
	s_lshl_b32 s32, s74, 8
	s_lshl_b32 s45, s27, 7
	s_lshl_b32 s63, s74, 1
	v_lshl_add_u32 v3, v1, 7, s32
	v_lshlrev_b32_e32 v3, 13, v3
	v_add_u32_e32 v4, s45, v2
	v_lshl_add_u32 v3, v4, 2, v3
	v_add_u32_e32 v7, s63, v1
	v_lshl_add_u32 v7, v7, 11, v4
	v_lshlrev_b32_e32 v7, 2, v7
	v_add_u32_e32 v24, 0x100000, v7
	s_mov_b64 s[76:77], s[92:93]
	s_add_u32 s78, s94, 0x100000
	s_addc_u32 s79, s95, 0
	global_load_dword v32, v3, s[76:77]
	s_add_u32 s76, s76, 0x2000
	s_addc_u32 s77, s77, 0
	global_load_dword v33, v3, s[76:77]
	s_add_u32 s76, s76, 0x2000
	s_addc_u32 s77, s77, 0
	global_load_dword v34, v3, s[76:77]
	s_add_u32 s76, s76, 0x2000
	s_addc_u32 s77, s77, 0
	global_load_dword v35, v3, s[76:77]
	s_add_u32 s76, s76, 0x2000
	s_addc_u32 s77, s77, 0
	global_load_dword v36, v3, s[76:77]
	s_add_u32 s76, s76, 0x2000
	s_addc_u32 s77, s77, 0
	global_load_dword v37, v3, s[76:77]
	s_add_u32 s76, s76, 0x2000
	s_addc_u32 s77, s77, 0
	global_load_dword v38, v3, s[76:77]
	s_add_u32 s76, s76, 0x2000
	s_addc_u32 s77, s77, 0
	global_load_dword v39, v3, s[76:77]
	s_add_u32 s76, s76, 0x2000
	s_addc_u32 s77, s77, 0
	global_load_dword v40, v3, s[76:77]
	s_add_u32 s76, s76, 0x2000
	s_addc_u32 s77, s77, 0
	global_load_dword v41, v3, s[76:77]
	s_add_u32 s76, s76, 0x2000
	s_addc_u32 s77, s77, 0
	global_load_dword v42, v3, s[76:77]
	s_add_u32 s76, s76, 0x2000
	s_addc_u32 s77, s77, 0
	global_load_dword v43, v3, s[76:77]
	s_add_u32 s76, s76, 0x2000
	s_addc_u32 s77, s77, 0
	global_load_dword v44, v3, s[76:77]
	s_add_u32 s76, s76, 0x2000
	s_addc_u32 s77, s77, 0
	global_load_dword v45, v3, s[76:77]
	s_add_u32 s76, s76, 0x2000
	s_addc_u32 s77, s77, 0
	global_load_dword v46, v3, s[76:77]
	s_add_u32 s76, s76, 0x2000
	s_addc_u32 s77, s77, 0
	global_load_dword v47, v3, s[76:77]
	s_add_u32 s76, s76, 0x2000
	s_addc_u32 s77, s77, 0
	global_load_dword v48, v3, s[76:77]
	s_add_u32 s76, s76, 0x2000
	s_addc_u32 s77, s77, 0
	global_load_dword v49, v3, s[76:77]
	s_add_u32 s76, s76, 0x2000
	s_addc_u32 s77, s77, 0
	global_load_dword v50, v3, s[76:77]
	s_add_u32 s76, s76, 0x2000
	s_addc_u32 s77, s77, 0
	global_load_dword v51, v3, s[76:77]
	s_add_u32 s76, s76, 0x2000
	s_addc_u32 s77, s77, 0
	global_load_dword v52, v3, s[76:77]
	s_add_u32 s76, s76, 0x2000
	s_addc_u32 s77, s77, 0
	global_load_dword v53, v3, s[76:77]
	s_add_u32 s76, s76, 0x2000
	s_addc_u32 s77, s77, 0
	global_load_dword v54, v3, s[76:77]
	s_add_u32 s76, s76, 0x2000
	s_addc_u32 s77, s77, 0
	global_load_dword v55, v3, s[76:77]
	s_add_u32 s76, s76, 0x2000
	s_addc_u32 s77, s77, 0
	global_load_dword v56, v3, s[76:77]
	s_add_u32 s76, s76, 0x2000
	s_addc_u32 s77, s77, 0
	global_load_dword v57, v3, s[76:77]
	s_add_u32 s76, s76, 0x2000
	s_addc_u32 s77, s77, 0
	global_load_dword v58, v3, s[76:77]
	s_add_u32 s76, s76, 0x2000
	s_addc_u32 s77, s77, 0
	global_load_dword v59, v3, s[76:77]
	s_add_u32 s76, s76, 0x2000
	s_addc_u32 s77, s77, 0
	global_load_dword v60, v3, s[76:77]
	s_add_u32 s76, s76, 0x2000
	s_addc_u32 s77, s77, 0
	global_load_dword v61, v3, s[76:77]
	s_add_u32 s76, s76, 0x2000
	s_addc_u32 s77, s77, 0
	global_load_dword v62, v3, s[76:77]
	s_add_u32 s76, s76, 0x2000
	s_addc_u32 s77, s77, 0
	global_load_dword v63, v3, s[76:77]
	s_add_u32 s76, s76, 0x2000
	s_addc_u32 s77, s77, 0
	v_mov_b32_e32 v5, 1.0
	v_mov_b32_e32 v6, 0
	s_waitcnt vmcnt(28)
	v_lshlrev_b32_e32 v8, 16, v32
	v_lshlrev_b32_e32 v10, 16, v33
	v_lshlrev_b32_e32 v12, 16, v34
	v_lshlrev_b32_e32 v14, 16, v35
	v_and_b32_e32 v9, 0xffff0000, v32
	v_and_b32_e32 v11, 0xffff0000, v33
	v_and_b32_e32 v13, 0xffff0000, v34
	v_and_b32_e32 v15, 0xffff0000, v35
	v_exp_f32_e32 v8, v8
	v_exp_f32_e32 v10, v10
	v_exp_f32_e32 v12, v12
	v_exp_f32_e32 v14, v14
	global_load_dword v32, v3, s[76:77]
	s_add_u32 s76, s76, 0x2000
	s_addc_u32 s77, s77, 0
	global_load_dword v33, v3, s[76:77]
	s_add_u32 s76, s76, 0x2000
	s_addc_u32 s77, s77, 0
	global_load_dword v34, v3, s[76:77]
	s_add_u32 s76, s76, 0x2000
	s_addc_u32 s77, s77, 0
	global_load_dword v35, v3, s[76:77]
	s_add_u32 s76, s76, 0x2000
	s_addc_u32 s77, s77, 0
	v_mul_f32_e32 v5, v5, v8
	v_fma_f32 v6, v6, v8, v9
	v_mul_f32_e32 v5, v5, v10
	v_fma_f32 v6, v6, v10, v11
	v_mul_f32_e32 v5, v5, v12
	v_fma_f32 v6, v6, v12, v13
	v_mul_f32_e32 v5, v5, v14
	v_fma_f32 v6, v6, v14, v15
	s_waitcnt vmcnt(28)
	v_lshlrev_b32_e32 v16, 16, v36
	v_lshlrev_b32_e32 v18, 16, v37
	v_lshlrev_b32_e32 v20, 16, v38
	v_lshlrev_b32_e32 v22, 16, v39
	v_and_b32_e32 v17, 0xffff0000, v36
	v_and_b32_e32 v19, 0xffff0000, v37
	v_and_b32_e32 v21, 0xffff0000, v38
	v_and_b32_e32 v23, 0xffff0000, v39
	v_exp_f32_e32 v16, v16
	v_exp_f32_e32 v18, v18
	v_exp_f32_e32 v20, v20
	v_exp_f32_e32 v22, v22
	global_load_dword v36, v3, s[76:77]
	s_add_u32 s76, s76, 0x2000
	s_addc_u32 s77, s77, 0
	global_load_dword v37, v3, s[76:77]
	s_add_u32 s76, s76, 0x2000
	s_addc_u32 s77, s77, 0
	global_load_dword v38, v3, s[76:77]
	s_add_u32 s76, s76, 0x2000
	s_addc_u32 s77, s77, 0
	global_load_dword v39, v3, s[76:77]
	s_add_u32 s76, s76, 0x2000
	s_addc_u32 s77, s77, 0
	v_mul_f32_e32 v5, v5, v16
	v_fma_f32 v6, v6, v16, v17
	v_mul_f32_e32 v5, v5, v18
	v_fma_f32 v6, v6, v18, v19
	v_mul_f32_e32 v5, v5, v20
	v_fma_f32 v6, v6, v20, v21
	v_mul_f32_e32 v5, v5, v22
	v_fma_f32 v6, v6, v22, v23
	s_waitcnt vmcnt(28)
; __device__ __forceinline__ float bf_lo(unsigned w) { return __uint_as_float(w << 16); }
; __device__ __forceinline__ float bf_hi(unsigned w) { return __uint_as_float(w & 0xffff0000u); }
; __global__ void __launch_bounds__(NTHR, 2) hybrid_block_fwd(Args a) {
;     ...
;         for (int i = 0; i < CH_L; ++i) { const u32x2 q = pab[(size_t)i * (LW / 2)];
;             const f32x2 av = (f32x2){__builtin_amdgcn_exp2f(bf_lo(q.x)), __builtin_amdgcn_exp2f(bf_lo(q.y))}, bv = (f32x2){bf_hi(q.x), bf_hi(q.y)}; P = P * av; H = av * H + bv; }
	v_lshlrev_b32_e32 v8, 16, v40
	v_lshlrev_b32_e32 v10, 16, v41
	v_lshlrev_b32_e32 v12, 16, v42
	v_lshlrev_b32_e32 v14, 16, v43
	v_and_b32_e32 v9, 0xffff0000, v40
	v_and_b32_e32 v11, 0xffff0000, v41
	v_and_b32_e32 v13, 0xffff0000, v42
	v_and_b32_e32 v15, 0xffff0000, v43
	v_exp_f32_e32 v8, v8
	v_exp_f32_e32 v10, v10
	v_exp_f32_e32 v12, v12
	v_exp_f32_e32 v14, v14
	global_load_dword v40, v3, s[76:77]
	s_add_u32 s76, s76, 0x2000
	s_addc_u32 s77, s77, 0
	global_load_dword v41, v3, s[76:77]
	s_add_u32 s76, s76, 0x2000
	s_addc_u32 s77, s77, 0
	global_load_dword v42, v3, s[76:77]
	s_add_u32 s76, s76, 0x2000
	s_addc_u32 s77, s77, 0
	global_load_dword v43, v3, s[76:77]
	s_add_u32 s76, s76, 0x2000
	s_addc_u32 s77, s77, 0
	v_mul_f32_e32 v5, v5, v8
	v_fma_f32 v6, v6, v8, v9
	v_mul_f32_e32 v5, v5, v10
	v_fma_f32 v6, v6, v10, v11
	v_mul_f32_e32 v5, v5, v12
	v_fma_f32 v6, v6, v12, v13
	v_mul_f32_e32 v5, v5, v14
	v_fma_f32 v6, v6, v14, v15
	s_waitcnt vmcnt(28)
	v_lshlrev_b32_e32 v16, 16, v44
	v_lshlrev_b32_e32 v18, 16, v45
	v_lshlrev_b32_e32 v20, 16, v46
	v_lshlrev_b32_e32 v22, 16, v47
	v_and_b32_e32 v17, 0xffff0000, v44
	v_and_b32_e32 v19, 0xffff0000, v45
	v_and_b32_e32 v21, 0xffff0000, v46
	v_and_b32_e32 v23, 0xffff0000, v47
	v_exp_f32_e32 v16, v16
	v_exp_f32_e32 v18, v18
	v_exp_f32_e32 v20, v20
	v_exp_f32_e32 v22, v22
	global_load_dword v44, v3, s[76:77]
	s_add_u32 s76, s76, 0x2000
	s_addc_u32 s77, s77, 0
	global_load_dword v45, v3, s[76:77]
	s_add_u32 s76, s76, 0x2000
	s_addc_u32 s77, s77, 0
	global_load_dword v46, v3, s[76:77]
	s_add_u32 s76, s76, 0x2000
	s_addc_u32 s77, s77, 0
	global_load_dword v47, v3, s[76:77]
	s_add_u32 s76, s76, 0x2000
	s_addc_u32 s77, s77, 0
	v_mul_f32_e32 v5, v5, v16
	v_fma_f32 v6, v6, v16, v17
	v_mul_f32_e32 v5, v5, v18
	v_fma_f32 v6, v6, v18, v19
	v_mul_f32_e32 v5, v5, v20
	v_fma_f32 v6, v6, v20, v21
	v_mul_f32_e32 v5, v5, v22
	v_fma_f32 v6, v6, v22, v23
	s_waitcnt vmcnt(28)
	v_lshlrev_b32_e32 v8, 16, v48
	v_lshlrev_b32_e32 v10, 16, v49
	v_lshlrev_b32_e32 v12, 16, v50
	v_lshlrev_b32_e32 v14, 16, v51
	v_and_b32_e32 v9, 0xffff0000, v48
	v_and_b32_e32 v11, 0xffff0000, v49
	v_and_b32_e32 v13, 0xffff0000, v50
	v_and_b32_e32 v15, 0xffff0000, v51
	v_exp_f32_e32 v8, v8
	v_exp_f32_e32 v10, v10
	v_exp_f32_e32 v12, v12
	v_exp_f32_e32 v14, v14
	global_load_dword v48, v3, s[76:77]
	s_add_u32 s76, s76, 0x2000
	s_addc_u32 s77, s77, 0
	global_load_dword v49, v3, s[76:77]
	s_add_u32 s76, s76, 0x2000
	s_addc_u32 s77, s77, 0
	global_load_dword v50, v3, s[76:77]
	s_add_u32 s76, s76, 0x2000
	s_addc_u32 s77, s77, 0
	global_load_dword v51, v3, s[76:77]
	s_add_u32 s76, s76, 0x2000
	s_addc_u32 s77, s77, 0
	v_mul_f32_e32 v5, v5, v8
	v_fma_f32 v6, v6, v8, v9
	v_mul_f32_e32 v5, v5, v10
	v_fma_f32 v6, v6, v10, v11
	v_mul_f32_e32 v5, v5, v12
	v_fma_f32 v6, v6, v12, v13
	v_mul_f32_e32 v5, v5, v14
	v_fma_f32 v6, v6, v14, v15
	s_waitcnt vmcnt(28)
	v_lshlrev_b32_e32 v16, 16, v52
	v_lshlrev_b32_e32 v18, 16, v53
	v_lshlrev_b32_e32 v20, 16, v54
	v_lshlrev_b32_e32 v22, 16, v55
	v_and_b32_e32 v17, 0xffff0000, v52
	v_and_b32_e32 v19, 0xffff0000, v53
	v_and_b32_e32 v21, 0xffff0000, v54
	v_and_b32_e32 v23, 0xffff0000, v55
	v_exp_f32_e32 v16, v16
	v_exp_f32_e32 v18, v18
	v_exp_f32_e32 v20, v20
	v_exp_f32_e32 v22, v22
	global_load_dword v52, v3, s[76:77]
	s_add_u32 s76, s76, 0x2000
	s_addc_u32 s77, s77, 0
	global_load_dword v53, v3, s[76:77]
	s_add_u32 s76, s76, 0x2000
	s_addc_u32 s77, s77, 0
	global_load_dword v54, v3, s[76:77]
	s_add_u32 s76, s76, 0x2000
	s_addc_u32 s77, s77, 0
	global_load_dword v55, v3, s[76:77]
	s_add_u32 s76, s76, 0x2000
	s_addc_u32 s77, s77, 0
	v_mul_f32_e32 v5, v5, v16
	v_fma_f32 v6, v6, v16, v17
	v_mul_f32_e32 v5, v5, v18
	v_fma_f32 v6, v6, v18, v19
	v_mul_f32_e32 v5, v5, v20
	v_fma_f32 v6, v6, v20, v21
	v_mul_f32_e32 v5, v5, v22
	v_fma_f32 v6, v6, v22, v23
	s_waitcnt vmcnt(28)
	v_lshlrev_b32_e32 v8, 16, v56
	v_lshlrev_b32_e32 v10, 16, v57
	v_lshlrev_b32_e32 v12, 16, v58
	v_lshlrev_b32_e32 v14, 16, v59
	v_and_b32_e32 v9, 0xffff0000, v56
	v_and_b32_e32 v11, 0xffff0000, v57
	v_and_b32_e32 v13, 0xffff0000, v58
	v_and_b32_e32 v15, 0xffff0000, v59
	v_exp_f32_e32 v8, v8
	v_exp_f32_e32 v10, v10
	v_exp_f32_e32 v12, v12
	v_exp_f32_e32 v14, v14
	global_load_dword v56, v3, s[76:77]
	s_add_u32 s76, s76, 0x2000
	s_addc_u32 s77, s77, 0
	global_load_dword v57, v3, s[76:77]
	s_add_u32 s76, s76, 0x2000
	s_addc_u32 s77, s77, 0
	global_load_dword v58, v3, s[76:77]
	s_add_u32 s76, s76, 0x2000
	s_addc_u32 s77, s77, 0
	global_load_dword v59, v3, s[76:77]
	s_add_u32 s76, s76, 0x2000
	s_addc_u32 s77, s77, 0
	v_mul_f32_e32 v5, v5, v8
	v_fma_f32 v6, v6, v8, v9
	v_mul_f32_e32 v5, v5, v10
	v_fma_f32 v6, v6, v10, v11
	v_mul_f32_e32 v5, v5, v12
	v_fma_f32 v6, v6, v12, v13
	v_mul_f32_e32 v5, v5, v14
	v_fma_f32 v6, v6, v14, v15
	s_waitcnt vmcnt(28)
	v_lshlrev_b32_e32 v16, 16, v60
	v_lshlrev_b32_e32 v18, 16, v61
	v_lshlrev_b32_e32 v20, 16, v62
	v_lshlrev_b32_e32 v22, 16, v63
	v_and_b32_e32 v17, 0xffff0000, v60
	v_and_b32_e32 v19, 0xffff0000, v61
	v_and_b32_e32 v21, 0xffff0000, v62
	v_and_b32_e32 v23, 0xffff0000, v63
	v_exp_f32_e32 v16, v16
	v_exp_f32_e32 v18, v18
	v_exp_f32_e32 v20, v20
	v_exp_f32_e32 v22, v22
	global_load_dword v60, v3, s[76:77]
	s_add_u32 s76, s76, 0x2000
	s_addc_u32 s77, s77, 0
	global_load_dword v61, v3, s[76:77]
	s_add_u32 s76, s76, 0x2000
	s_addc_u32 s77, s77, 0
	global_load_dword v62, v3, s[76:77]
	s_add_u32 s76, s76, 0x2000
	s_addc_u32 s77, s77, 0
	global_load_dword v63, v3, s[76:77]
	s_add_u32 s76, s76, 0x2000
	s_addc_u32 s77, s77, 0
	v_mul_f32_e32 v5, v5, v16
	v_fma_f32 v6, v6, v16, v17
	v_mul_f32_e32 v5, v5, v18
	v_fma_f32 v6, v6, v18, v19
	v_mul_f32_e32 v5, v5, v20
	v_fma_f32 v6, v6, v20, v21
	v_mul_f32_e32 v5, v5, v22
	v_fma_f32 v6, v6, v22, v23
	s_waitcnt vmcnt(28)
; __device__ __forceinline__ float bf_lo(unsigned w) { return __uint_as_float(w << 16); }
; __device__ __forceinline__ float bf_hi(unsigned w) { return __uint_as_float(w & 0xffff0000u); }
; __global__ void __launch_bounds__(NTHR, 2) hybrid_block_fwd(Args a) {
;     ...
;         for (int i = 0; i < CH_L; ++i) { const u32x2 q = pab[(size_t)i * (LW / 2)];
;             const f32x2 av = (f32x2){__builtin_amdgcn_exp2f(bf_lo(q.x)), __builtin_amdgcn_exp2f(bf_lo(q.y))}, bv = (f32x2){bf_hi(q.x), bf_hi(q.y)}; P = P * av; H = av * H + bv; }
	v_lshlrev_b32_e32 v8, 16, v32
	v_lshlrev_b32_e32 v10, 16, v33
	v_lshlrev_b32_e32 v12, 16, v34
	v_lshlrev_b32_e32 v14, 16, v35
	v_and_b32_e32 v9, 0xffff0000, v32
	v_and_b32_e32 v11, 0xffff0000, v33
	v_and_b32_e32 v13, 0xffff0000, v34
	v_and_b32_e32 v15, 0xffff0000, v35
	v_exp_f32_e32 v8, v8
	v_exp_f32_e32 v10, v10
	v_exp_f32_e32 v12, v12
	v_exp_f32_e32 v14, v14
	global_load_dword v32, v3, s[76:77]
	s_add_u32 s76, s76, 0x2000
	s_addc_u32 s77, s77, 0
	global_load_dword v33, v3, s[76:77]
	s_add_u32 s76, s76, 0x2000
	s_addc_u32 s77, s77, 0
	global_load_dword v34, v3, s[76:77]
	s_add_u32 s76, s76, 0x2000
	s_addc_u32 s77, s77, 0
	global_load_dword v35, v3, s[76:77]
	s_add_u32 s76, s76, 0x2000
	s_addc_u32 s77, s77, 0
	v_mul_f32_e32 v5, v5, v8
	v_fma_f32 v6, v6, v8, v9
	v_mul_f32_e32 v5, v5, v10
	v_fma_f32 v6, v6, v10, v11
	v_mul_f32_e32 v5, v5, v12
	v_fma_f32 v6, v6, v12, v13
	v_mul_f32_e32 v5, v5, v14
	v_fma_f32 v6, v6, v14, v15
	s_waitcnt vmcnt(28)
	v_lshlrev_b32_e32 v16, 16, v36
	v_lshlrev_b32_e32 v18, 16, v37
	v_lshlrev_b32_e32 v20, 16, v38
	v_lshlrev_b32_e32 v22, 16, v39
	v_and_b32_e32 v17, 0xffff0000, v36
	v_and_b32_e32 v19, 0xffff0000, v37
	v_and_b32_e32 v21, 0xffff0000, v38
	v_and_b32_e32 v23, 0xffff0000, v39
	v_exp_f32_e32 v16, v16
	v_exp_f32_e32 v18, v18
	v_exp_f32_e32 v20, v20
	v_exp_f32_e32 v22, v22
	global_load_dword v36, v3, s[76:77]
	s_add_u32 s76, s76, 0x2000
	s_addc_u32 s77, s77, 0
	global_load_dword v37, v3, s[76:77]
	s_add_u32 s76, s76, 0x2000
	s_addc_u32 s77, s77, 0
	global_load_dword v38, v3, s[76:77]
	s_add_u32 s76, s76, 0x2000
	s_addc_u32 s77, s77, 0
	global_load_dword v39, v3, s[76:77]
	s_add_u32 s76, s76, 0x2000
	s_addc_u32 s77, s77, 0
	v_mul_f32_e32 v5, v5, v16
	v_fma_f32 v6, v6, v16, v17
	v_mul_f32_e32 v5, v5, v18
	v_fma_f32 v6, v6, v18, v19
	v_mul_f32_e32 v5, v5, v20
	v_fma_f32 v6, v6, v20, v21
	v_mul_f32_e32 v5, v5, v22
	v_fma_f32 v6, v6, v22, v23
	s_waitcnt vmcnt(28)
	v_lshlrev_b32_e32 v8, 16, v40
	v_lshlrev_b32_e32 v10, 16, v41
	v_lshlrev_b32_e32 v12, 16, v42
	v_lshlrev_b32_e32 v14, 16, v43
	v_and_b32_e32 v9, 0xffff0000, v40
	v_and_b32_e32 v11, 0xffff0000, v41
	v_and_b32_e32 v13, 0xffff0000, v42
	v_and_b32_e32 v15, 0xffff0000, v43
	v_exp_f32_e32 v8, v8
	v_exp_f32_e32 v10, v10
	v_exp_f32_e32 v12, v12
	v_exp_f32_e32 v14, v14
	global_load_dword v40, v3, s[76:77]
	s_add_u32 s76, s76, 0x2000
	s_addc_u32 s77, s77, 0
	global_load_dword v41, v3, s[76:77]
	s_add_u32 s76, s76, 0x2000
	s_addc_u32 s77, s77, 0
	global_load_dword v42, v3, s[76:77]
	s_add_u32 s76, s76, 0x2000
	s_addc_u32 s77, s77, 0
	global_load_dword v43, v3, s[76:77]
	s_add_u32 s76, s76, 0x2000
	s_addc_u32 s77, s77, 0
	v_mul_f32_e32 v5, v5, v8
	v_fma_f32 v6, v6, v8, v9
	v_mul_f32_e32 v5, v5, v10
	v_fma_f32 v6, v6, v10, v11
	v_mul_f32_e32 v5, v5, v12
	v_fma_f32 v6, v6, v12, v13
	v_mul_f32_e32 v5, v5, v14
	v_fma_f32 v6, v6, v14, v15
	s_waitcnt vmcnt(28)
	v_lshlrev_b32_e32 v16, 16, v44
	v_lshlrev_b32_e32 v18, 16, v45
	v_lshlrev_b32_e32 v20, 16, v46
	v_lshlrev_b32_e32 v22, 16, v47
	v_and_b32_e32 v17, 0xffff0000, v44
	v_and_b32_e32 v19, 0xffff0000, v45
	v_and_b32_e32 v21, 0xffff0000, v46
	v_and_b32_e32 v23, 0xffff0000, v47
	v_exp_f32_e32 v16, v16
	v_exp_f32_e32 v18, v18
	v_exp_f32_e32 v20, v20
	v_exp_f32_e32 v22, v22
	global_load_dword v44, v3, s[76:77]
	s_add_u32 s76, s76, 0x2000
	s_addc_u32 s77, s77, 0
	global_load_dword v45, v3, s[76:77]
	s_add_u32 s76, s76, 0x2000
	s_addc_u32 s77, s77, 0
	global_load_dword v46, v3, s[76:77]
	s_add_u32 s76, s76, 0x2000
	s_addc_u32 s77, s77, 0
	global_load_dword v47, v3, s[76:77]
	s_add_u32 s76, s76, 0x2000
	s_addc_u32 s77, s77, 0
	v_mul_f32_e32 v5, v5, v16
	v_fma_f32 v6, v6, v16, v17
	v_mul_f32_e32 v5, v5, v18
	v_fma_f32 v6, v6, v18, v19
	v_mul_f32_e32 v5, v5, v20
	v_fma_f32 v6, v6, v20, v21
	v_mul_f32_e32 v5, v5, v22
	v_fma_f32 v6, v6, v22, v23
	s_waitcnt vmcnt(28)
	v_lshlrev_b32_e32 v8, 16, v48
	v_lshlrev_b32_e32 v10, 16, v49
	v_lshlrev_b32_e32 v12, 16, v50
	v_lshlrev_b32_e32 v14, 16, v51
	v_and_b32_e32 v9, 0xffff0000, v48
	v_and_b32_e32 v11, 0xffff0000, v49
	v_and_b32_e32 v13, 0xffff0000, v50
	v_and_b32_e32 v15, 0xffff0000, v51
	v_exp_f32_e32 v8, v8
	v_exp_f32_e32 v10, v10
	v_exp_f32_e32 v12, v12
	v_exp_f32_e32 v14, v14
	global_load_dword v48, v3, s[76:77]
	s_add_u32 s76, s76, 0x2000
	s_addc_u32 s77, s77, 0
	global_load_dword v49, v3, s[76:77]
	s_add_u32 s76, s76, 0x2000
	s_addc_u32 s77, s77, 0
	global_load_dword v50, v3, s[76:77]
	s_add_u32 s76, s76, 0x2000
	s_addc_u32 s77, s77, 0
	global_load_dword v51, v3, s[76:77]
	s_add_u32 s76, s76, 0x2000
	s_addc_u32 s77, s77, 0
	v_mul_f32_e32 v5, v5, v8
	v_fma_f32 v6, v6, v8, v9
	v_mul_f32_e32 v5, v5, v10
	v_fma_f32 v6, v6, v10, v11
	v_mul_f32_e32 v5, v5, v12
	v_fma_f32 v6, v6, v12, v13
	v_mul_f32_e32 v5, v5, v14
	v_fma_f32 v6, v6, v14, v15
	s_waitcnt vmcnt(28)
	v_lshlrev_b32_e32 v16, 16, v52
	v_lshlrev_b32_e32 v18, 16, v53
	v_lshlrev_b32_e32 v20, 16, v54
	v_lshlrev_b32_e32 v22, 16, v55
	v_and_b32_e32 v17, 0xffff0000, v52
	v_and_b32_e32 v19, 0xffff0000, v53
	v_and_b32_e32 v21, 0xffff0000, v54
	v_and_b32_e32 v23, 0xffff0000, v55
	v_exp_f32_e32 v16, v16
	v_exp_f32_e32 v18, v18
	v_exp_f32_e32 v20, v20
	v_exp_f32_e32 v22, v22
	global_load_dword v52, v3, s[76:77]
	s_add_u32 s76, s76, 0x2000
	s_addc_u32 s77, s77, 0
	global_load_dword v53, v3, s[76:77]
	s_add_u32 s76, s76, 0x2000
	s_addc_u32 s77, s77, 0
	global_load_dword v54, v3, s[76:77]
	s_add_u32 s76, s76, 0x2000
	s_addc_u32 s77, s77, 0
	global_load_dword v55, v3, s[76:77]
	s_add_u32 s76, s76, 0x2000
	s_addc_u32 s77, s77, 0
	v_mul_f32_e32 v5, v5, v16
	v_fma_f32 v6, v6, v16, v17
	v_mul_f32_e32 v5, v5, v18
	v_fma_f32 v6, v6, v18, v19
	v_mul_f32_e32 v5, v5, v20
	v_fma_f32 v6, v6, v20, v21
	v_mul_f32_e32 v5, v5, v22
	v_fma_f32 v6, v6, v22, v23
	s_waitcnt vmcnt(28)
; __device__ __forceinline__ float bf_lo(unsigned w) { return __uint_as_float(w << 16); }
; __device__ __forceinline__ float bf_hi(unsigned w) { return __uint_as_float(w & 0xffff0000u); }
; __global__ void __launch_bounds__(NTHR, 2) hybrid_block_fwd(Args a) {
;     ...
;         for (int i = 0; i < CH_L; ++i) { const u32x2 q = pab[(size_t)i * (LW / 2)];
;             const f32x2 av = (f32x2){__builtin_amdgcn_exp2f(bf_lo(q.x)), __builtin_amdgcn_exp2f(bf_lo(q.y))}, bv = (f32x2){bf_hi(q.x), bf_hi(q.y)}; P = P * av; H = av * H + bv; }
	v_lshlrev_b32_e32 v8, 16, v56
	v_lshlrev_b32_e32 v10, 16, v57
	v_lshlrev_b32_e32 v12, 16, v58
	v_lshlrev_b32_e32 v14, 16, v59
	v_and_b32_e32 v9, 0xffff0000, v56
	v_and_b32_e32 v11, 0xffff0000, v57
	v_and_b32_e32 v13, 0xffff0000, v58
	v_and_b32_e32 v15, 0xffff0000, v59
	v_exp_f32_e32 v8, v8
	v_exp_f32_e32 v10, v10
	v_exp_f32_e32 v12, v12
	v_exp_f32_e32 v14, v14
	global_load_dword v56, v3, s[76:77]
	s_add_u32 s76, s76, 0x2000
	s_addc_u32 s77, s77, 0
	global_load_dword v57, v3, s[76:77]
	s_add_u32 s76, s76, 0x2000
	s_addc_u32 s77, s77, 0
	global_load_dword v58, v3, s[76:77]
	s_add_u32 s76, s76, 0x2000
	s_addc_u32 s77, s77, 0
	global_load_dword v59, v3, s[76:77]
	s_add_u32 s76, s76, 0x2000
	s_addc_u32 s77, s77, 0
	v_mul_f32_e32 v5, v5, v8
	v_fma_f32 v6, v6, v8, v9
	v_mul_f32_e32 v5, v5, v10
	v_fma_f32 v6, v6, v10, v11
	v_mul_f32_e32 v5, v5, v12
	v_fma_f32 v6, v6, v12, v13
	v_mul_f32_e32 v5, v5, v14
	v_fma_f32 v6, v6, v14, v15
	s_waitcnt vmcnt(28)
	v_lshlrev_b32_e32 v16, 16, v60
	v_lshlrev_b32_e32 v18, 16, v61
	v_lshlrev_b32_e32 v20, 16, v62
	v_lshlrev_b32_e32 v22, 16, v63
	v_and_b32_e32 v17, 0xffff0000, v60
	v_and_b32_e32 v19, 0xffff0000, v61
	v_and_b32_e32 v21, 0xffff0000, v62
	v_and_b32_e32 v23, 0xffff0000, v63
	v_exp_f32_e32 v16, v16
	v_exp_f32_e32 v18, v18
	v_exp_f32_e32 v20, v20
	v_exp_f32_e32 v22, v22
	global_load_dword v60, v3, s[76:77]
	s_add_u32 s76, s76, 0x2000
	s_addc_u32 s77, s77, 0
	global_load_dword v61, v3, s[76:77]
	s_add_u32 s76, s76, 0x2000
	s_addc_u32 s77, s77, 0
	global_load_dword v62, v3, s[76:77]
	s_add_u32 s76, s76, 0x2000
	s_addc_u32 s77, s77, 0
	global_load_dword v63, v3, s[76:77]
	s_add_u32 s76, s76, 0x2000
	s_addc_u32 s77, s77, 0
	v_mul_f32_e32 v5, v5, v16
	v_fma_f32 v6, v6, v16, v17
	v_mul_f32_e32 v5, v5, v18
	v_fma_f32 v6, v6, v18, v19
	v_mul_f32_e32 v5, v5, v20
	v_fma_f32 v6, v6, v20, v21
	v_mul_f32_e32 v5, v5, v22
	v_fma_f32 v6, v6, v22, v23
	s_waitcnt vmcnt(28)
	v_lshlrev_b32_e32 v8, 16, v32
	v_lshlrev_b32_e32 v10, 16, v33
	v_lshlrev_b32_e32 v12, 16, v34
	v_lshlrev_b32_e32 v14, 16, v35
	v_and_b32_e32 v9, 0xffff0000, v32
	v_and_b32_e32 v11, 0xffff0000, v33
	v_and_b32_e32 v13, 0xffff0000, v34
	v_and_b32_e32 v15, 0xffff0000, v35
	v_exp_f32_e32 v8, v8
	v_exp_f32_e32 v10, v10
	v_exp_f32_e32 v12, v12
	v_exp_f32_e32 v14, v14
	global_load_dword v32, v3, s[76:77]
	s_add_u32 s76, s76, 0x2000
	s_addc_u32 s77, s77, 0
	global_load_dword v33, v3, s[76:77]
	s_add_u32 s76, s76, 0x2000
	s_addc_u32 s77, s77, 0
	global_load_dword v34, v3, s[76:77]
	s_add_u32 s76, s76, 0x2000
	s_addc_u32 s77, s77, 0
	global_load_dword v35, v3, s[76:77]
	s_add_u32 s76, s76, 0x2000
	s_addc_u32 s77, s77, 0
	v_mul_f32_e32 v5, v5, v8
	v_fma_f32 v6, v6, v8, v9
	v_mul_f32_e32 v5, v5, v10
	v_fma_f32 v6, v6, v10, v11
	v_mul_f32_e32 v5, v5, v12
	v_fma_f32 v6, v6, v12, v13
	v_mul_f32_e32 v5, v5, v14
	v_fma_f32 v6, v6, v14, v15
	s_waitcnt vmcnt(28)
	v_lshlrev_b32_e32 v16, 16, v36
	v_lshlrev_b32_e32 v18, 16, v37
	v_lshlrev_b32_e32 v20, 16, v38
	v_lshlrev_b32_e32 v22, 16, v39
	v_and_b32_e32 v17, 0xffff0000, v36
	v_and_b32_e32 v19, 0xffff0000, v37
	v_and_b32_e32 v21, 0xffff0000, v38
	v_and_b32_e32 v23, 0xffff0000, v39
	v_exp_f32_e32 v16, v16
	v_exp_f32_e32 v18, v18
	v_exp_f32_e32 v20, v20
	v_exp_f32_e32 v22, v22
	global_load_dword v36, v3, s[76:77]
	s_add_u32 s76, s76, 0x2000
	s_addc_u32 s77, s77, 0
	global_load_dword v37, v3, s[76:77]
	s_add_u32 s76, s76, 0x2000
	s_addc_u32 s77, s77, 0
	global_load_dword v38, v3, s[76:77]
	s_add_u32 s76, s76, 0x2000
	s_addc_u32 s77, s77, 0
	global_load_dword v39, v3, s[76:77]
	s_add_u32 s76, s76, 0x2000
	s_addc_u32 s77, s77, 0
	v_mul_f32_e32 v5, v5, v16
	v_fma_f32 v6, v6, v16, v17
	v_mul_f32_e32 v5, v5, v18
	v_fma_f32 v6, v6, v18, v19
	v_mul_f32_e32 v5, v5, v20
	v_fma_f32 v6, v6, v20, v21
	v_mul_f32_e32 v5, v5, v22
	v_fma_f32 v6, v6, v22, v23
	s_waitcnt vmcnt(28)
	v_lshlrev_b32_e32 v8, 16, v40
	v_lshlrev_b32_e32 v10, 16, v41
	v_lshlrev_b32_e32 v12, 16, v42
	v_lshlrev_b32_e32 v14, 16, v43
	v_and_b32_e32 v9, 0xffff0000, v40
	v_and_b32_e32 v11, 0xffff0000, v41
	v_and_b32_e32 v13, 0xffff0000, v42
	v_and_b32_e32 v15, 0xffff0000, v43
	v_exp_f32_e32 v8, v8
	v_exp_f32_e32 v10, v10
	v_exp_f32_e32 v12, v12
	v_exp_f32_e32 v14, v14
	global_load_dword v40, v3, s[76:77]
	s_add_u32 s76, s76, 0x2000
	s_addc_u32 s77, s77, 0
	global_load_dword v41, v3, s[76:77]
	s_add_u32 s76, s76, 0x2000
	s_addc_u32 s77, s77, 0
	global_load_dword v42, v3, s[76:77]
	s_add_u32 s76, s76, 0x2000
	s_addc_u32 s77, s77, 0
	global_load_dword v43, v3, s[76:77]
	s_add_u32 s76, s76, 0x2000
	s_addc_u32 s77, s77, 0
	v_mul_f32_e32 v5, v5, v8
	v_fma_f32 v6, v6, v8, v9
	v_mul_f32_e32 v5, v5, v10
	v_fma_f32 v6, v6, v10, v11
	v_mul_f32_e32 v5, v5, v12
	v_fma_f32 v6, v6, v12, v13
	v_mul_f32_e32 v5, v5, v14
	v_fma_f32 v6, v6, v14, v15
	s_waitcnt vmcnt(28)
	v_lshlrev_b32_e32 v16, 16, v44
	v_lshlrev_b32_e32 v18, 16, v45
	v_lshlrev_b32_e32 v20, 16, v46
	v_lshlrev_b32_e32 v22, 16, v47
	v_and_b32_e32 v17, 0xffff0000, v44
	v_and_b32_e32 v19, 0xffff0000, v45
	v_and_b32_e32 v21, 0xffff0000, v46
	v_and_b32_e32 v23, 0xffff0000, v47
	v_exp_f32_e32 v16, v16
	v_exp_f32_e32 v18, v18
	v_exp_f32_e32 v20, v20
	v_exp_f32_e32 v22, v22
	global_load_dword v44, v3, s[76:77]
	s_add_u32 s76, s76, 0x2000
	s_addc_u32 s77, s77, 0
	global_load_dword v45, v3, s[76:77]
	s_add_u32 s76, s76, 0x2000
	s_addc_u32 s77, s77, 0
	global_load_dword v46, v3, s[76:77]
	s_add_u32 s76, s76, 0x2000
	s_addc_u32 s77, s77, 0
	global_load_dword v47, v3, s[76:77]
	s_add_u32 s76, s76, 0x2000
	s_addc_u32 s77, s77, 0
	v_mul_f32_e32 v5, v5, v16
	v_fma_f32 v6, v6, v16, v17
	v_mul_f32_e32 v5, v5, v18
	v_fma_f32 v6, v6, v18, v19
	v_mul_f32_e32 v5, v5, v20
	v_fma_f32 v6, v6, v20, v21
	v_mul_f32_e32 v5, v5, v22
	v_fma_f32 v6, v6, v22, v23
	s_waitcnt vmcnt(28)
; __device__ __forceinline__ float bf_lo(unsigned w) { return __uint_as_float(w << 16); }
; __device__ __forceinline__ float bf_hi(unsigned w) { return __uint_as_float(w & 0xffff0000u); }
; __global__ void __launch_bounds__(NTHR, 2) hybrid_block_fwd(Args a) {
;     ...
;         for (int i = 0; i < CH_L; ++i) { const u32x2 q = pab[(size_t)i * (LW / 2)];
;             const f32x2 av = (f32x2){__builtin_amdgcn_exp2f(bf_lo(q.x)), __builtin_amdgcn_exp2f(bf_lo(q.y))}, bv = (f32x2){bf_hi(q.x), bf_hi(q.y)}; P = P * av; H = av * H + bv; }
	v_lshlrev_b32_e32 v8, 16, v48
	v_lshlrev_b32_e32 v10, 16, v49
	v_lshlrev_b32_e32 v12, 16, v50
	v_lshlrev_b32_e32 v14, 16, v51
	v_and_b32_e32 v9, 0xffff0000, v48
	v_and_b32_e32 v11, 0xffff0000, v49
	v_and_b32_e32 v13, 0xffff0000, v50
	v_and_b32_e32 v15, 0xffff0000, v51
	v_exp_f32_e32 v8, v8
	v_exp_f32_e32 v10, v10
	v_exp_f32_e32 v12, v12
	v_exp_f32_e32 v14, v14
	global_load_dword v48, v3, s[76:77]
	s_add_u32 s76, s76, 0x2000
	s_addc_u32 s77, s77, 0
	global_load_dword v49, v3, s[76:77]
	s_add_u32 s76, s76, 0x2000
	s_addc_u32 s77, s77, 0
	global_load_dword v50, v3, s[76:77]
	s_add_u32 s76, s76, 0x2000
	s_addc_u32 s77, s77, 0
	global_load_dword v51, v3, s[76:77]
	s_add_u32 s76, s76, 0x2000
	s_addc_u32 s77, s77, 0
	v_mul_f32_e32 v5, v5, v8
	v_fma_f32 v6, v6, v8, v9
	v_mul_f32_e32 v5, v5, v10
	v_fma_f32 v6, v6, v10, v11
	v_mul_f32_e32 v5, v5, v12
	v_fma_f32 v6, v6, v12, v13
	v_mul_f32_e32 v5, v5, v14
	v_fma_f32 v6, v6, v14, v15
	s_waitcnt vmcnt(28)
	v_lshlrev_b32_e32 v16, 16, v52
	v_lshlrev_b32_e32 v18, 16, v53
	v_lshlrev_b32_e32 v20, 16, v54
	v_lshlrev_b32_e32 v22, 16, v55
	v_and_b32_e32 v17, 0xffff0000, v52
	v_and_b32_e32 v19, 0xffff0000, v53
	v_and_b32_e32 v21, 0xffff0000, v54
	v_and_b32_e32 v23, 0xffff0000, v55
	v_exp_f32_e32 v16, v16
	v_exp_f32_e32 v18, v18
	v_exp_f32_e32 v20, v20
	v_exp_f32_e32 v22, v22
	global_load_dword v52, v3, s[76:77]
	s_add_u32 s76, s76, 0x2000
	s_addc_u32 s77, s77, 0
	global_load_dword v53, v3, s[76:77]
	s_add_u32 s76, s76, 0x2000
	s_addc_u32 s77, s77, 0
	global_load_dword v54, v3, s[76:77]
	s_add_u32 s76, s76, 0x2000
	s_addc_u32 s77, s77, 0
	global_load_dword v55, v3, s[76:77]
	s_add_u32 s76, s76, 0x2000
	s_addc_u32 s77, s77, 0
	v_mul_f32_e32 v5, v5, v16
	v_fma_f32 v6, v6, v16, v17
	v_mul_f32_e32 v5, v5, v18
	v_fma_f32 v6, v6, v18, v19
	v_mul_f32_e32 v5, v5, v20
	v_fma_f32 v6, v6, v20, v21
	v_mul_f32_e32 v5, v5, v22
	v_fma_f32 v6, v6, v22, v23
	s_waitcnt vmcnt(28)
	v_lshlrev_b32_e32 v8, 16, v56
	v_lshlrev_b32_e32 v10, 16, v57
	v_lshlrev_b32_e32 v12, 16, v58
	v_lshlrev_b32_e32 v14, 16, v59
	v_and_b32_e32 v9, 0xffff0000, v56
	v_and_b32_e32 v11, 0xffff0000, v57
	v_and_b32_e32 v13, 0xffff0000, v58
	v_and_b32_e32 v15, 0xffff0000, v59
	v_exp_f32_e32 v8, v8
	v_exp_f32_e32 v10, v10
	v_exp_f32_e32 v12, v12
	v_exp_f32_e32 v14, v14
	global_load_dword v56, v3, s[76:77]
	s_add_u32 s76, s76, 0x2000
	s_addc_u32 s77, s77, 0
	global_load_dword v57, v3, s[76:77]
	s_add_u32 s76, s76, 0x2000
	s_addc_u32 s77, s77, 0
	global_load_dword v58, v3, s[76:77]
	s_add_u32 s76, s76, 0x2000
	s_addc_u32 s77, s77, 0
	global_load_dword v59, v3, s[76:77]
	s_add_u32 s76, s76, 0x2000
	s_addc_u32 s77, s77, 0
	v_mul_f32_e32 v5, v5, v8
	v_fma_f32 v6, v6, v8, v9
	v_mul_f32_e32 v5, v5, v10
	v_fma_f32 v6, v6, v10, v11
	v_mul_f32_e32 v5, v5, v12
	v_fma_f32 v6, v6, v12, v13
	v_mul_f32_e32 v5, v5, v14
	v_fma_f32 v6, v6, v14, v15
	s_waitcnt vmcnt(28)
	v_lshlrev_b32_e32 v16, 16, v60
	v_lshlrev_b32_e32 v18, 16, v61
	v_lshlrev_b32_e32 v20, 16, v62
	v_lshlrev_b32_e32 v22, 16, v63
	v_and_b32_e32 v17, 0xffff0000, v60
	v_and_b32_e32 v19, 0xffff0000, v61
	v_and_b32_e32 v21, 0xffff0000, v62
	v_and_b32_e32 v23, 0xffff0000, v63
	v_exp_f32_e32 v16, v16
	v_exp_f32_e32 v18, v18
	v_exp_f32_e32 v20, v20
	v_exp_f32_e32 v22, v22
	global_load_dword v60, v3, s[76:77]
	s_add_u32 s76, s76, 0x2000
	s_addc_u32 s77, s77, 0
	global_load_dword v61, v3, s[76:77]
	s_add_u32 s76, s76, 0x2000
	s_addc_u32 s77, s77, 0
	global_load_dword v62, v3, s[76:77]
	s_add_u32 s76, s76, 0x2000
	s_addc_u32 s77, s77, 0
	global_load_dword v63, v3, s[76:77]
	s_add_u32 s76, s76, 0x2000
	s_addc_u32 s77, s77, 0
	v_mul_f32_e32 v5, v5, v16
	v_fma_f32 v6, v6, v16, v17
	v_mul_f32_e32 v5, v5, v18
	v_fma_f32 v6, v6, v18, v19
	v_mul_f32_e32 v5, v5, v20
	v_fma_f32 v6, v6, v20, v21
	v_mul_f32_e32 v5, v5, v22
	v_fma_f32 v6, v6, v22, v23
	s_waitcnt vmcnt(28)
	v_lshlrev_b32_e32 v8, 16, v32
	v_lshlrev_b32_e32 v10, 16, v33
	v_lshlrev_b32_e32 v12, 16, v34
	v_lshlrev_b32_e32 v14, 16, v35
	v_and_b32_e32 v9, 0xffff0000, v32
	v_and_b32_e32 v11, 0xffff0000, v33
	v_and_b32_e32 v13, 0xffff0000, v34
	v_and_b32_e32 v15, 0xffff0000, v35
	v_exp_f32_e32 v8, v8
	v_exp_f32_e32 v10, v10
	v_exp_f32_e32 v12, v12
	v_exp_f32_e32 v14, v14
	v_mul_f32_e32 v5, v5, v8
	v_fma_f32 v6, v6, v8, v9
	v_mul_f32_e32 v5, v5, v10
	v_fma_f32 v6, v6, v10, v11
	v_mul_f32_e32 v5, v5, v12
	v_fma_f32 v6, v6, v12, v13
	v_mul_f32_e32 v5, v5, v14
	v_fma_f32 v6, v6, v14, v15
	s_waitcnt vmcnt(24)
; __device__ __forceinline__ float bf_lo(unsigned w) { return __uint_as_float(w << 16); }
; __device__ __forceinline__ float bf_hi(unsigned w) { return __uint_as_float(w & 0xffff0000u); }
; __global__ void __launch_bounds__(NTHR, 2) hybrid_block_fwd(Args a) {
;     ...
;         for (int i = 0; i < CH_L; ++i) { const u32x2 q = pab[(size_t)i * (LW / 2)];
;             const f32x2 av = (f32x2){__builtin_amdgcn_exp2f(bf_lo(q.x)), __builtin_amdgcn_exp2f(bf_lo(q.y))}, bv = (f32x2){bf_hi(q.x), bf_hi(q.y)}; P = P * av; H = av * H + bv; }
;         ((f32x2*)(AGGP + (size_t)(b * NCH + chunk) * LW))[c2] = P; ((f32x2*)(AGGH + (size_t)(b * NCH + chunk) * LW))[c2] = H;
	v_lshlrev_b32_e32 v16, 16, v36
	v_lshlrev_b32_e32 v18, 16, v37
	v_lshlrev_b32_e32 v20, 16, v38
	v_lshlrev_b32_e32 v22, 16, v39
	v_and_b32_e32 v17, 0xffff0000, v36
	v_and_b32_e32 v19, 0xffff0000, v37
	v_and_b32_e32 v21, 0xffff0000, v38
	v_and_b32_e32 v23, 0xffff0000, v39
	v_exp_f32_e32 v16, v16
	v_exp_f32_e32 v18, v18
	v_exp_f32_e32 v20, v20
	v_exp_f32_e32 v22, v22
	v_mul_f32_e32 v5, v5, v16
	v_fma_f32 v6, v6, v16, v17
	v_mul_f32_e32 v5, v5, v18
	v_fma_f32 v6, v6, v18, v19
	v_mul_f32_e32 v5, v5, v20
	v_fma_f32 v6, v6, v20, v21
	v_mul_f32_e32 v5, v5, v22
	v_fma_f32 v6, v6, v22, v23
	s_waitcnt vmcnt(20)
	v_lshlrev_b32_e32 v8, 16, v40
	v_lshlrev_b32_e32 v10, 16, v41
	v_lshlrev_b32_e32 v12, 16, v42
	v_lshlrev_b32_e32 v14, 16, v43
	v_and_b32_e32 v9, 0xffff0000, v40
	v_and_b32_e32 v11, 0xffff0000, v41
	v_and_b32_e32 v13, 0xffff0000, v42
	v_and_b32_e32 v15, 0xffff0000, v43
	v_exp_f32_e32 v8, v8
	v_exp_f32_e32 v10, v10
	v_exp_f32_e32 v12, v12
	v_exp_f32_e32 v14, v14
	v_mul_f32_e32 v5, v5, v8
	v_fma_f32 v6, v6, v8, v9
	v_mul_f32_e32 v5, v5, v10
	v_fma_f32 v6, v6, v10, v11
	v_mul_f32_e32 v5, v5, v12
	v_fma_f32 v6, v6, v12, v13
	v_mul_f32_e32 v5, v5, v14
	v_fma_f32 v6, v6, v14, v15
	s_waitcnt vmcnt(16)
	v_lshlrev_b32_e32 v16, 16, v44
	v_lshlrev_b32_e32 v18, 16, v45
	v_lshlrev_b32_e32 v20, 16, v46
	v_lshlrev_b32_e32 v22, 16, v47
	v_and_b32_e32 v17, 0xffff0000, v44
	v_and_b32_e32 v19, 0xffff0000, v45
	v_and_b32_e32 v21, 0xffff0000, v46
	v_and_b32_e32 v23, 0xffff0000, v47
	v_exp_f32_e32 v16, v16
	v_exp_f32_e32 v18, v18
	v_exp_f32_e32 v20, v20
	v_exp_f32_e32 v22, v22
	v_mul_f32_e32 v5, v5, v16
	v_fma_f32 v6, v6, v16, v17
	v_mul_f32_e32 v5, v5, v18
	v_fma_f32 v6, v6, v18, v19
	v_mul_f32_e32 v5, v5, v20
	v_fma_f32 v6, v6, v20, v21
	v_mul_f32_e32 v5, v5, v22
	v_fma_f32 v6, v6, v22, v23
	s_waitcnt vmcnt(12)
	v_lshlrev_b32_e32 v8, 16, v48
	v_lshlrev_b32_e32 v10, 16, v49
	v_lshlrev_b32_e32 v12, 16, v50
	v_lshlrev_b32_e32 v14, 16, v51
	v_and_b32_e32 v9, 0xffff0000, v48
	v_and_b32_e32 v11, 0xffff0000, v49
	v_and_b32_e32 v13, 0xffff0000, v50
	v_and_b32_e32 v15, 0xffff0000, v51
	v_exp_f32_e32 v8, v8
	v_exp_f32_e32 v10, v10
	v_exp_f32_e32 v12, v12
	v_exp_f32_e32 v14, v14
	v_mul_f32_e32 v5, v5, v8
	v_fma_f32 v6, v6, v8, v9
	v_mul_f32_e32 v5, v5, v10
	v_fma_f32 v6, v6, v10, v11
	v_mul_f32_e32 v5, v5, v12
	v_fma_f32 v6, v6, v12, v13
	v_mul_f32_e32 v5, v5, v14
	v_fma_f32 v6, v6, v14, v15
	s_waitcnt vmcnt(8)
	v_lshlrev_b32_e32 v16, 16, v52
	v_lshlrev_b32_e32 v18, 16, v53
	v_lshlrev_b32_e32 v20, 16, v54
	v_lshlrev_b32_e32 v22, 16, v55
	v_and_b32_e32 v17, 0xffff0000, v52
	v_and_b32_e32 v19, 0xffff0000, v53
	v_and_b32_e32 v21, 0xffff0000, v54
	v_and_b32_e32 v23, 0xffff0000, v55
	v_exp_f32_e32 v16, v16
	v_exp_f32_e32 v18, v18
	v_exp_f32_e32 v20, v20
	v_exp_f32_e32 v22, v22
	v_mul_f32_e32 v5, v5, v16
	v_fma_f32 v6, v6, v16, v17
	v_mul_f32_e32 v5, v5, v18
	v_fma_f32 v6, v6, v18, v19
	v_mul_f32_e32 v5, v5, v20
	v_fma_f32 v6, v6, v20, v21
	v_mul_f32_e32 v5, v5, v22
	v_fma_f32 v6, v6, v22, v23
	s_waitcnt vmcnt(4)
	v_lshlrev_b32_e32 v8, 16, v56
	v_lshlrev_b32_e32 v10, 16, v57
	v_lshlrev_b32_e32 v12, 16, v58
	v_lshlrev_b32_e32 v14, 16, v59
	v_and_b32_e32 v9, 0xffff0000, v56
	v_and_b32_e32 v11, 0xffff0000, v57
	v_and_b32_e32 v13, 0xffff0000, v58
	v_and_b32_e32 v15, 0xffff0000, v59
	v_exp_f32_e32 v8, v8
	v_exp_f32_e32 v10, v10
	v_exp_f32_e32 v12, v12
	v_exp_f32_e32 v14, v14
	v_mul_f32_e32 v5, v5, v8
	v_fma_f32 v6, v6, v8, v9
	v_mul_f32_e32 v5, v5, v10
	v_fma_f32 v6, v6, v10, v11
	v_mul_f32_e32 v5, v5, v12
	v_fma_f32 v6, v6, v12, v13
	v_mul_f32_e32 v5, v5, v14
	v_fma_f32 v6, v6, v14, v15
	s_waitcnt vmcnt(0)
	v_lshlrev_b32_e32 v16, 16, v60
	v_lshlrev_b32_e32 v18, 16, v61
	v_lshlrev_b32_e32 v20, 16, v62
	v_lshlrev_b32_e32 v22, 16, v63
	v_and_b32_e32 v17, 0xffff0000, v60
	v_and_b32_e32 v19, 0xffff0000, v61
	v_and_b32_e32 v21, 0xffff0000, v62
	v_and_b32_e32 v23, 0xffff0000, v63
	v_exp_f32_e32 v16, v16
	v_exp_f32_e32 v18, v18
	v_exp_f32_e32 v20, v20
	v_exp_f32_e32 v22, v22
	v_mul_f32_e32 v5, v5, v16
	v_fma_f32 v6, v6, v16, v17
	v_mul_f32_e32 v5, v5, v18
	v_fma_f32 v6, v6, v18, v19
	v_mul_f32_e32 v5, v5, v20
	v_fma_f32 v6, v6, v20, v21
	v_mul_f32_e32 v5, v5, v22
	v_fma_f32 v6, v6, v22, v23
	global_store_dword v7, v5, s[78:79]
	global_store_dword v24, v6, s[78:79]
